# P2 v-tile epilogue: pV stores as full 128B lines (lane-pair DPP exchange of the two adjacent 64B halves)
# speedup vs baseline: 1.0047x; 1.0047x over previous
; __device__ __forceinline__ float gelu_tanh(float x) { const float u = 1.5957691216f * (x + 0.044715f * x * x * x); return x * __builtin_amdgcn_rcpf(1.f + __expf(-u)); }
; __device__ __forceinline__ void st_bf16x8(bf16_t* p, const f32x4 a, const f32x4 b) { uint4 o; o.x = cvt_pk_bf16(a[0], a[1]); o.y = cvt_pk_bf16(a[2], a[3]); o.z = cvt_pk_bf16(b[0], b[1]); o.w = cvt_pk_bf16(b[2], b[3]); *(uint4*)p = o; }
;     __device__ __forceinline__ void row(const f32x4 (&a)[2][2], int row, int pn, int wc, int fq) const {
;     ...
;         } else if (pn < 4) {
;             const int head = (pn - 2) * 4 + wc;
;             f32x4 g[2][2]; float ss = 0.f;
; #pragma unroll
;             for (int bj = 0; bj < 2; ++bj)
; #pragma unroll
;                 for (int n = 0; n < 2; ++n)
; #pragma unroll
;                     for (int j = 0; j < 4; ++j) { const float t = gelu_tanh(a[bj][n][j]); g[bj][n][j] = t; ss += t * t; }
;             ss += __shfl_xor(ss, 16); ss += __shfl_xor(ss, 32);
;             const float rs = rsqrtf(ss * (1.f / 64.f) + EPS);
; #pragma unroll
;             for (int bj = 0; bj < 2; ++bj) { const int d = head * 64 + bj * 32 + 8 * fq;
;                 const f32x4 v0 = g[bj][0] * rs * *(const f32x4*)(g_v + d), v1 = g[bj][1] * rs * *(const f32x4*)(g_v + d + 4);
;                 st_bf16x8(pV + (size_t)row * 512 + d, v0, v1);
;                 if (row >= NP && row < NTOK) { float* o = out + O_VS + (size_t)(row - NP) * 512 + d; *(f32x4*)o = v0; *(f32x4*)(o + 4) = v1; } }
.LBB0_218:
	s_andn2_b64 vcc, exec, s[0:1]
	s_cbranch_vccnz .LBB0_223
	v_mov_b32_e32 v190, 0x3d372713
	v_mov_b32_e32 v192, 0xbfcc422a
	v_mov_b32_e32 v194, 0x3fb8aa3b
	v_pk_mul_f32 v[128:129], v[124:125], v[190:191] op_sel_hi:[1,0]
	v_pk_mul_f32 v[132:133], v[126:127], v[190:191] op_sel_hi:[1,0]
	v_pk_mul_f32 v[158:159], v[120:121], v[190:191] op_sel_hi:[1,0]
	v_pk_mul_f32 v[160:161], v[122:123], v[190:191] op_sel_hi:[1,0]
	v_pk_mul_f32 v[162:163], v[116:117], v[190:191] op_sel_hi:[1,0]
	v_pk_mul_f32 v[164:165], v[118:119], v[190:191] op_sel_hi:[1,0]
	v_pk_mul_f32 v[166:167], v[112:113], v[190:191] op_sel_hi:[1,0]
	v_pk_mul_f32 v[168:169], v[114:115], v[190:191] op_sel_hi:[1,0]
	v_pk_mul_f32 v[128:129], v[124:125], v[128:129]
	v_pk_mul_f32 v[132:133], v[126:127], v[132:133]
	v_pk_mul_f32 v[158:159], v[120:121], v[158:159]
	v_pk_mul_f32 v[160:161], v[122:123], v[160:161]
	v_pk_mul_f32 v[162:163], v[116:117], v[162:163]
	v_pk_mul_f32 v[164:165], v[118:119], v[164:165]
	v_pk_mul_f32 v[166:167], v[112:113], v[166:167]
	v_pk_mul_f32 v[168:169], v[114:115], v[168:169]
	v_pk_fma_f32 v[128:129], v[124:125], v[128:129], v[124:125]
	v_pk_fma_f32 v[132:133], v[126:127], v[132:133], v[126:127]
	v_pk_fma_f32 v[158:159], v[120:121], v[158:159], v[120:121]
	v_pk_fma_f32 v[160:161], v[122:123], v[160:161], v[122:123]
	v_pk_fma_f32 v[162:163], v[116:117], v[162:163], v[116:117]
	v_pk_fma_f32 v[164:165], v[118:119], v[164:165], v[118:119]
	v_pk_fma_f32 v[166:167], v[112:113], v[166:167], v[112:113]
	v_pk_fma_f32 v[168:169], v[114:115], v[168:169], v[114:115]
	v_pk_mul_f32 v[128:129], v[128:129], v[192:193] op_sel_hi:[1,0]
	v_pk_mul_f32 v[132:133], v[132:133], v[192:193] op_sel_hi:[1,0]
	v_pk_mul_f32 v[158:159], v[158:159], v[192:193] op_sel_hi:[1,0]
	v_pk_mul_f32 v[160:161], v[160:161], v[192:193] op_sel_hi:[1,0]
	v_pk_mul_f32 v[162:163], v[162:163], v[192:193] op_sel_hi:[1,0]
	v_pk_mul_f32 v[164:165], v[164:165], v[192:193] op_sel_hi:[1,0]
	v_pk_mul_f32 v[166:167], v[166:167], v[192:193] op_sel_hi:[1,0]
	v_pk_mul_f32 v[168:169], v[168:169], v[192:193] op_sel_hi:[1,0]
	v_pk_mul_f32 v[128:129], v[128:129], v[194:195] op_sel_hi:[1,0]
	v_pk_mul_f32 v[132:133], v[132:133], v[194:195] op_sel_hi:[1,0]
	v_pk_mul_f32 v[158:159], v[158:159], v[194:195] op_sel_hi:[1,0]
	v_pk_mul_f32 v[160:161], v[160:161], v[194:195] op_sel_hi:[1,0]
	v_pk_mul_f32 v[162:163], v[162:163], v[194:195] op_sel_hi:[1,0]
	v_pk_mul_f32 v[164:165], v[164:165], v[194:195] op_sel_hi:[1,0]
	v_pk_mul_f32 v[166:167], v[166:167], v[194:195] op_sel_hi:[1,0]
	v_pk_mul_f32 v[168:169], v[168:169], v[194:195] op_sel_hi:[1,0]
	v_exp_f32_e32 v128, v128
	v_exp_f32_e32 v129, v129
	v_exp_f32_e32 v132, v132
	v_exp_f32_e32 v133, v133
	v_exp_f32_e32 v158, v158
	v_exp_f32_e32 v159, v159
	v_exp_f32_e32 v160, v160
	v_exp_f32_e32 v161, v161
	v_exp_f32_e32 v162, v162
	v_exp_f32_e32 v163, v163
	v_exp_f32_e32 v164, v164
	v_exp_f32_e32 v165, v165
	v_exp_f32_e32 v166, v166
	v_exp_f32_e32 v167, v167
	v_exp_f32_e32 v168, v168
	v_exp_f32_e32 v169, v169
	v_pk_add_f32 v[128:129], v[128:129], 1.0 op_sel_hi:[1,0]
	v_pk_add_f32 v[132:133], v[132:133], 1.0 op_sel_hi:[1,0]
	v_pk_add_f32 v[158:159], v[158:159], 1.0 op_sel_hi:[1,0]
	v_pk_add_f32 v[160:161], v[160:161], 1.0 op_sel_hi:[1,0]
	v_pk_add_f32 v[162:163], v[162:163], 1.0 op_sel_hi:[1,0]
	v_pk_add_f32 v[164:165], v[164:165], 1.0 op_sel_hi:[1,0]
	v_pk_add_f32 v[166:167], v[166:167], 1.0 op_sel_hi:[1,0]
	v_pk_add_f32 v[168:169], v[168:169], 1.0 op_sel_hi:[1,0]
	v_rcp_f32_e32 v128, v128
	v_rcp_f32_e32 v129, v129
	v_rcp_f32_e32 v132, v132
	v_rcp_f32_e32 v133, v133
	v_rcp_f32_e32 v158, v158
	v_rcp_f32_e32 v159, v159
	v_rcp_f32_e32 v160, v160
	v_rcp_f32_e32 v161, v161
	v_rcp_f32_e32 v162, v162
	v_rcp_f32_e32 v163, v163
	v_rcp_f32_e32 v164, v164
	v_rcp_f32_e32 v165, v165
	v_rcp_f32_e32 v166, v166
	v_rcp_f32_e32 v167, v167
	v_rcp_f32_e32 v168, v168
	v_rcp_f32_e32 v169, v169
	v_pk_mul_f32 v[128:129], v[124:125], v[128:129]
	v_pk_mul_f32 v[132:133], v[126:127], v[132:133]
	v_pk_mul_f32 v[158:159], v[120:121], v[158:159]
	v_pk_mul_f32 v[160:161], v[122:123], v[160:161]
	v_pk_mul_f32 v[162:163], v[116:117], v[162:163]
	v_pk_mul_f32 v[164:165], v[118:119], v[164:165]
	v_pk_mul_f32 v[166:167], v[112:113], v[166:167]
	v_pk_mul_f32 v[168:169], v[114:115], v[168:169]
	v_pk_mul_f32 v[130:131], v[128:129], v[128:129]
	v_pk_mul_f32 v[134:135], v[132:133], v[132:133]
	v_add_f32_e32 v130, v130, v131
	v_add_f32_e32 v130, v134, v130
	v_pk_mul_f32 v[170:171], v[158:159], v[158:159]
	v_add_f32_e32 v130, v135, v130
	v_add_f32_e32 v130, v170, v130
	v_pk_mul_f32 v[172:173], v[160:161], v[160:161]
	v_add_f32_e32 v130, v171, v130
	v_add_f32_e32 v130, v172, v130
	v_pk_mul_f32 v[174:175], v[162:163], v[162:163]
	v_add_f32_e32 v130, v173, v130
	v_add_f32_e32 v130, v130, v174
	v_pk_mul_f32 v[176:177], v[164:165], v[164:165]
	v_add_f32_e32 v130, v175, v130
	v_add_f32_e32 v130, v176, v130
	v_pk_mul_f32 v[178:179], v[166:167], v[166:167]
	v_add_f32_e32 v130, v177, v130
	v_add_f32_e32 v130, v178, v130
	v_pk_mul_f32 v[180:181], v[168:169], v[168:169]
	v_add_f32_e32 v130, v179, v130
	v_add_f32_e32 v130, v180, v130
	v_add_f32_e32 v130, v181, v130
	ds_bpermute_b32 v131, v229, v130
	v_lshl_add_u64 v[180:181], v[140:141], 2, s[18:19]
	v_ashrrev_i32_e32 v157, 31, v156
	v_lshlrev_b64 v[174:175], 10, v[156:157]
	v_lshlrev_b32_e32 v172, 9, v156
	s_waitcnt lgkmcnt(0)
	v_add_f32_e32 v130, v130, v131
	ds_bpermute_b32 v131, v230, v130
	v_mov_b32_e32 v173, v141
	v_cndmask_b32_e64 v157, 0, 1, s[10:11]
	v_cmp_ne_u32_e64 s[0:1], 1, v157
	s_waitcnt lgkmcnt(0)
	v_add_f32_e32 v130, v130, v131
	v_fmamk_f32 v130, v130, 0x3c800000, v188
	v_cmp_gt_f32_e32 vcc, s13, v130
	v_mul_f32_e32 v131, 0x4b800000, v130
	s_nop 0
	v_cndmask_b32_e32 v130, v130, v131, vcc
	v_rsq_f32_e32 v130, v130
	s_nop 0
	v_mul_f32_e32 v131, 0x45800000, v130
	v_cndmask_b32_e32 v170, v130, v131, vcc
	v_pk_mul_f32 v[176:177], v[128:129], v[170:171] op_sel_hi:[1,0]
	v_pk_mul_f32 v[178:179], v[132:133], v[170:171] op_sel_hi:[1,0]
	s_waitcnt vmcnt(0)
	v_mov_b64_e32 v[128:129], v[208:209]
	v_mov_b64_e32 v[130:131], v[210:211]
	v_mov_b64_e32 v[132:133], v[204:205]
	v_mov_b64_e32 v[134:135], v[206:207]
	v_pk_mul_f32 v[158:159], v[158:159], v[170:171] op_sel_hi:[1,0]
	v_pk_mul_f32 v[160:161], v[160:161], v[170:171] op_sel_hi:[1,0]
	s_andn2_b64 vcc, exec, s[10:11]
	v_pk_mul_f32 v[128:129], v[128:129], v[158:159]
	v_lshl_add_u64 v[158:159], s[46:47], 0, v[174:175]
	v_pk_mul_f32 v[134:135], v[134:135], v[178:179]
	v_pk_mul_f32 v[132:133], v[132:133], v[176:177]
	v_pk_mul_f32 v[130:131], v[130:131], v[160:161]
	v_lshl_add_u64 v[158:159], v[140:141], 1, v[158:159]
	v_lshl_add_u64 v[160:161], v[172:173], 2, s[56:57]
	v_cvt_pk_bf16_f32 v174, v132, v133
	v_cvt_pk_bf16_f32 v175, v134, v135
	v_cvt_pk_bf16_f32 v176, v128, v129
	v_cvt_pk_bf16_f32 v177, v130, v131
	v_mov_b64_e32 v[196:197], v[174:175]
	v_mov_b64_e32 v[198:199], v[176:177]
	s_cbranch_vccnz .LBB0_221
; __device__ __forceinline__ void st_bf16x8(bf16_t* p, const f32x4 a, const f32x4 b) { uint4 o; o.x = cvt_pk_bf16(a[0], a[1]); o.y = cvt_pk_bf16(a[2], a[3]); o.z = cvt_pk_bf16(b[0], b[1]); o.w = cvt_pk_bf16(b[2], b[3]); *(uint4*)p = o; }
;     __device__ __forceinline__ void row(const f32x4 (&a)[2][2], int row, int pn, int wc, int fq) const {
;     ...
;             for (int bj = 0; bj < 2; ++bj) { const int d = head * 64 + bj * 32 + 8 * fq;
;                 const f32x4 v0 = g[bj][0] * rs * *(const f32x4*)(g_v + d), v1 = g[bj][1] * rs * *(const f32x4*)(g_v + d + 4);
;                 st_bf16x8(pV + (size_t)row * 512 + d, v0, v1);
;                 if (row >= NP && row < NTOK) { float* o = out + O_VS + (size_t)(row - NP) * 512 + d; *(f32x4*)o = v0; *(f32x4*)(o + 4) = v1; } }
	v_lshl_add_u64 v[172:173], v[140:141], 2, v[160:161]
	v_lshl_add_u64 v[174:175], v[172:173], 0, s[70:71]
	v_add_co_u32_e32 v172, vcc, 0x2108000, v172
	s_nop 1
	v_addc_co_u32_e32 v173, vcc, 0, v173, vcc
	global_store_dwordx4 v[172:173], v[132:135], off
	global_store_dwordx4 v[174:175], v[128:131], off offset:16
.LBB0_221:
	v_mov_b64_e32 v[128:129], v[212:213]
	v_mov_b64_e32 v[130:131], v[214:215]
	s_nop 0
	v_mov_b64_e32 v[132:133], v[216:217]
	v_mov_b64_e32 v[134:135], v[218:219]
	v_mov_b32_e32 v171, v170
	v_mov_b32_e32 v172, v170
	v_mov_b32_e32 v173, v170
	v_pk_mul_f32 v[162:163], v[162:163], v[170:171]
	v_pk_mul_f32 v[164:165], v[164:165], v[172:173]
	v_pk_mul_f32 v[166:167], v[166:167], v[170:171]
	v_pk_mul_f32 v[168:169], v[168:169], v[172:173]
	s_and_b64 vcc, exec, s[0:1]
	v_pk_mul_f32 v[130:131], v[164:165], v[130:131]
	v_pk_mul_f32 v[128:129], v[162:163], v[128:129]
	v_pk_mul_f32 v[134:135], v[168:169], v[134:135]
	v_pk_mul_f32 v[132:133], v[166:167], v[132:133]
	v_cvt_pk_bf16_f32 v162, v128, v129
	v_cvt_pk_bf16_f32 v163, v130, v131
	v_cvt_pk_bf16_f32 v165, v134, v135
	s_nop 0
	v_cvt_pk_bf16_f32 v164, v132, v133
	s_mov_b64 s[100:101], vcc
	v_and_b32_e32 v222, 1, v156
	s_movk_i32 s32, 0xfc40
	v_mad_i64_i32 v[158:159], s[98:99], v222, s32, v[158:159]
	v_cmp_eq_u32_e32 vcc, 0, v222
	s_nop 1
	v_cndmask_b32_dpp v200, v162, v196, vcc quad_perm:[1,0,3,2] row_mask:0xf bank_mask:0xf
	v_cndmask_b32_dpp v201, v163, v197, vcc quad_perm:[1,0,3,2] row_mask:0xf bank_mask:0xf
	v_cndmask_b32_dpp v202, v164, v198, vcc quad_perm:[1,0,3,2] row_mask:0xf bank_mask:0xf
	v_cndmask_b32_dpp v203, v165, v199, vcc quad_perm:[1,0,3,2] row_mask:0xf bank_mask:0xf
	v_cmp_ne_u32_e32 vcc, 0, v222
	s_nop 1
	v_cndmask_b32_dpp v162, v196, v162, vcc quad_perm:[1,0,3,2] row_mask:0xf bank_mask:0xf
	v_cndmask_b32_dpp v163, v197, v163, vcc quad_perm:[1,0,3,2] row_mask:0xf bank_mask:0xf
	v_cndmask_b32_dpp v164, v198, v164, vcc quad_perm:[1,0,3,2] row_mask:0xf bank_mask:0xf
	v_cndmask_b32_dpp v165, v199, v165, vcc quad_perm:[1,0,3,2] row_mask:0xf bank_mask:0xf
	global_store_dwordx4 v[158:159], v[200:203], off
	global_store_dwordx4 v[158:159], v[162:165], off offset:1024
	s_mov_b64 vcc, s[100:101]
	s_cbranch_vccnz .LBB0_223
	v_lshl_add_u64 v[158:159], v[152:153], 2, v[160:161]
	v_lshl_add_u64 v[160:161], v[158:159], 0, s[70:71]
	v_add_co_u32_e32 v158, vcc, 0x2108000, v158
	s_nop 1
	v_addc_co_u32_e32 v159, vcc, 0, v159, vcc
	global_store_dwordx4 v[158:159], v[128:131], off
	global_store_dwordx4 v[160:161], v[132:135], off offset:16

; __device__ __forceinline__ float gelu_tanh(float x) { const float u = 1.5957691216f * (x + 0.044715f * x * x * x); return x * __builtin_amdgcn_rcpf(1.f + __expf(-u)); }
; __device__ __forceinline__ void st_bf16x8(bf16_t* p, const f32x4 a, const f32x4 b) { uint4 o; o.x = cvt_pk_bf16(a[0], a[1]); o.y = cvt_pk_bf16(a[2], a[3]); o.z = cvt_pk_bf16(b[0], b[1]); o.w = cvt_pk_bf16(b[2], b[3]); *(uint4*)p = o; }
;     __device__ __forceinline__ void row(const f32x4 (&a)[2][2], int row, int pn, int wc, int fq) const {
;     ...
;             const int head = (pn - 2) * 4 + wc;
;             f32x4 g[2][2]; float ss = 0.f;
; #pragma unroll
;             for (int bj = 0; bj < 2; ++bj)
; #pragma unroll
;                 for (int n = 0; n < 2; ++n)
; #pragma unroll
;                     for (int j = 0; j < 4; ++j) { const float t = gelu_tanh(a[bj][n][j]); g[bj][n][j] = t; ss += t * t; }
;             ss += __shfl_xor(ss, 16); ss += __shfl_xor(ss, 32);
;             const float rs = rsqrtf(ss * (1.f / 64.f) + EPS);
; #pragma unroll
;             for (int bj = 0; bj < 2; ++bj) { const int d = head * 64 + bj * 32 + 8 * fq;
;                 const f32x4 v0 = g[bj][0] * rs * *(const f32x4*)(g_v + d), v1 = g[bj][1] * rs * *(const f32x4*)(g_v + d + 4);
;                 st_bf16x8(pV + (size_t)row * 512 + d, v0, v1);
.LBB0_240:
	s_andn2_b64 vcc, exec, s[0:1]
	s_cbranch_vccnz .LBB0_245
	v_mov_b32_e32 v190, 0x3d372713
	v_mov_b32_e32 v192, 0xbfcc422a
	v_mov_b32_e32 v194, 0x3fb8aa3b
	v_pk_mul_f32 v[112:113], v[108:109], v[190:191] op_sel_hi:[1,0]
	v_pk_mul_f32 v[116:117], v[110:111], v[190:191] op_sel_hi:[1,0]
	v_pk_mul_f32 v[122:123], v[104:105], v[190:191] op_sel_hi:[1,0]
	v_pk_mul_f32 v[124:125], v[106:107], v[190:191] op_sel_hi:[1,0]
	v_pk_mul_f32 v[126:127], v[100:101], v[190:191] op_sel_hi:[1,0]
	v_pk_mul_f32 v[128:129], v[102:103], v[190:191] op_sel_hi:[1,0]
	v_pk_mul_f32 v[130:131], v[96:97], v[190:191] op_sel_hi:[1,0]
	v_pk_mul_f32 v[132:133], v[98:99], v[190:191] op_sel_hi:[1,0]
	v_pk_mul_f32 v[112:113], v[108:109], v[112:113]
	v_pk_mul_f32 v[116:117], v[110:111], v[116:117]
	v_pk_mul_f32 v[122:123], v[104:105], v[122:123]
	v_pk_mul_f32 v[124:125], v[106:107], v[124:125]
	v_pk_mul_f32 v[126:127], v[100:101], v[126:127]
	v_pk_mul_f32 v[128:129], v[102:103], v[128:129]
	v_pk_mul_f32 v[130:131], v[96:97], v[130:131]
	v_pk_mul_f32 v[132:133], v[98:99], v[132:133]
	v_pk_fma_f32 v[112:113], v[108:109], v[112:113], v[108:109]
	v_pk_fma_f32 v[116:117], v[110:111], v[116:117], v[110:111]
	v_pk_fma_f32 v[122:123], v[104:105], v[122:123], v[104:105]
	v_pk_fma_f32 v[124:125], v[106:107], v[124:125], v[106:107]
	v_pk_fma_f32 v[126:127], v[100:101], v[126:127], v[100:101]
	v_pk_fma_f32 v[128:129], v[102:103], v[128:129], v[102:103]
	v_pk_fma_f32 v[130:131], v[96:97], v[130:131], v[96:97]
	v_pk_fma_f32 v[132:133], v[98:99], v[132:133], v[98:99]
	v_pk_mul_f32 v[112:113], v[112:113], v[192:193] op_sel_hi:[1,0]
	v_pk_mul_f32 v[116:117], v[116:117], v[192:193] op_sel_hi:[1,0]
	v_pk_mul_f32 v[122:123], v[122:123], v[192:193] op_sel_hi:[1,0]
	v_pk_mul_f32 v[124:125], v[124:125], v[192:193] op_sel_hi:[1,0]
	v_pk_mul_f32 v[126:127], v[126:127], v[192:193] op_sel_hi:[1,0]
	v_pk_mul_f32 v[128:129], v[128:129], v[192:193] op_sel_hi:[1,0]
	v_pk_mul_f32 v[130:131], v[130:131], v[192:193] op_sel_hi:[1,0]
	v_pk_mul_f32 v[132:133], v[132:133], v[192:193] op_sel_hi:[1,0]
	v_pk_mul_f32 v[112:113], v[112:113], v[194:195] op_sel_hi:[1,0]
	v_pk_mul_f32 v[116:117], v[116:117], v[194:195] op_sel_hi:[1,0]
	v_pk_mul_f32 v[122:123], v[122:123], v[194:195] op_sel_hi:[1,0]
	v_pk_mul_f32 v[124:125], v[124:125], v[194:195] op_sel_hi:[1,0]
	v_pk_mul_f32 v[126:127], v[126:127], v[194:195] op_sel_hi:[1,0]
	v_pk_mul_f32 v[128:129], v[128:129], v[194:195] op_sel_hi:[1,0]
	v_pk_mul_f32 v[130:131], v[130:131], v[194:195] op_sel_hi:[1,0]
	v_pk_mul_f32 v[132:133], v[132:133], v[194:195] op_sel_hi:[1,0]
	v_exp_f32_e32 v112, v112
	v_exp_f32_e32 v113, v113
	v_exp_f32_e32 v116, v116
	v_exp_f32_e32 v117, v117
	v_exp_f32_e32 v122, v122
	v_exp_f32_e32 v123, v123
	v_exp_f32_e32 v124, v124
	v_exp_f32_e32 v125, v125
	v_exp_f32_e32 v126, v126
	v_exp_f32_e32 v127, v127
	v_exp_f32_e32 v128, v128
	v_exp_f32_e32 v129, v129
	v_exp_f32_e32 v130, v130
	v_exp_f32_e32 v131, v131
	v_exp_f32_e32 v132, v132
	v_exp_f32_e32 v133, v133
	v_pk_add_f32 v[112:113], v[112:113], 1.0 op_sel_hi:[1,0]
	v_pk_add_f32 v[116:117], v[116:117], 1.0 op_sel_hi:[1,0]
	v_pk_add_f32 v[122:123], v[122:123], 1.0 op_sel_hi:[1,0]
	v_pk_add_f32 v[124:125], v[124:125], 1.0 op_sel_hi:[1,0]
	v_pk_add_f32 v[126:127], v[126:127], 1.0 op_sel_hi:[1,0]
	v_pk_add_f32 v[128:129], v[128:129], 1.0 op_sel_hi:[1,0]
	v_pk_add_f32 v[130:131], v[130:131], 1.0 op_sel_hi:[1,0]
	v_pk_add_f32 v[132:133], v[132:133], 1.0 op_sel_hi:[1,0]
	v_rcp_f32_e32 v112, v112
	v_rcp_f32_e32 v113, v113
	v_rcp_f32_e32 v116, v116
	v_rcp_f32_e32 v117, v117
	v_rcp_f32_e32 v122, v122
	v_rcp_f32_e32 v123, v123
	v_rcp_f32_e32 v124, v124
	v_rcp_f32_e32 v125, v125
	v_rcp_f32_e32 v126, v126
	v_rcp_f32_e32 v127, v127
	v_rcp_f32_e32 v128, v128
	v_rcp_f32_e32 v129, v129
	v_rcp_f32_e32 v130, v130
	v_rcp_f32_e32 v131, v131
	v_rcp_f32_e32 v132, v132
	v_rcp_f32_e32 v133, v133
	v_pk_mul_f32 v[112:113], v[108:109], v[112:113]
	v_pk_mul_f32 v[116:117], v[110:111], v[116:117]
	v_pk_mul_f32 v[122:123], v[104:105], v[122:123]
	v_pk_mul_f32 v[124:125], v[106:107], v[124:125]
	v_pk_mul_f32 v[126:127], v[100:101], v[126:127]
	v_pk_mul_f32 v[128:129], v[102:103], v[128:129]
	v_pk_mul_f32 v[130:131], v[96:97], v[130:131]
	v_pk_mul_f32 v[132:133], v[98:99], v[132:133]
	v_pk_mul_f32 v[114:115], v[112:113], v[112:113]
	v_pk_mul_f32 v[118:119], v[116:117], v[116:117]
	v_add_f32_e32 v114, v114, v115
	v_add_f32_e32 v114, v118, v114
	v_pk_mul_f32 v[134:135], v[122:123], v[122:123]
	v_add_f32_e32 v114, v119, v114
	v_add_f32_e32 v114, v134, v114
	v_pk_mul_f32 v[158:159], v[124:125], v[124:125]
	v_add_f32_e32 v114, v135, v114
	v_add_f32_e32 v114, v158, v114
	v_pk_mul_f32 v[160:161], v[126:127], v[126:127]
	v_add_f32_e32 v114, v159, v114
	v_add_f32_e32 v114, v114, v160
	v_pk_mul_f32 v[162:163], v[128:129], v[128:129]
	v_add_f32_e32 v114, v161, v114
	v_add_f32_e32 v114, v162, v114
	v_pk_mul_f32 v[164:165], v[130:131], v[130:131]
	v_add_f32_e32 v114, v163, v114
	v_add_f32_e32 v114, v164, v114
	v_pk_mul_f32 v[166:167], v[132:133], v[132:133]
	v_add_f32_e32 v114, v165, v114
	v_add_f32_e32 v114, v166, v114
	v_add_f32_e32 v114, v167, v114
	ds_bpermute_b32 v115, v229, v114
	v_lshl_add_u64 v[166:167], v[140:141], 2, s[18:19]
	v_ashrrev_i32_e32 v121, 31, v120
	v_lshlrev_b64 v[160:161], 10, v[120:121]
	v_lshlrev_b32_e32 v158, 9, v120
	s_waitcnt lgkmcnt(0)
	v_add_f32_e32 v114, v114, v115
	ds_bpermute_b32 v115, v230, v114
	v_mov_b32_e32 v159, v141
	v_cndmask_b32_e64 v121, 0, 1, s[10:11]
	v_cmp_ne_u32_e64 s[0:1], 1, v121
	s_waitcnt lgkmcnt(0)
	v_add_f32_e32 v114, v114, v115
	v_fmamk_f32 v114, v114, 0x3c800000, v188
	v_cmp_gt_f32_e32 vcc, s13, v114
	v_mul_f32_e32 v115, 0x4b800000, v114
	s_nop 0
	v_cndmask_b32_e32 v114, v114, v115, vcc
	v_rsq_f32_e32 v114, v114
	s_nop 0
	v_mul_f32_e32 v115, 0x45800000, v114
	v_cndmask_b32_e32 v134, v114, v115, vcc
	v_pk_mul_f32 v[162:163], v[112:113], v[134:135] op_sel_hi:[1,0]
	v_pk_mul_f32 v[164:165], v[116:117], v[134:135] op_sel_hi:[1,0]
	v_mov_b64_e32 v[112:113], v[208:209]
	v_mov_b64_e32 v[114:115], v[210:211]
	v_mov_b64_e32 v[116:117], v[204:205]
	v_mov_b64_e32 v[118:119], v[206:207]
	v_pk_mul_f32 v[122:123], v[122:123], v[134:135] op_sel_hi:[1,0]
	v_pk_mul_f32 v[124:125], v[124:125], v[134:135] op_sel_hi:[1,0]
	s_andn2_b64 vcc, exec, s[10:11]
	v_pk_mul_f32 v[112:113], v[112:113], v[122:123]
	v_lshl_add_u64 v[122:123], s[46:47], 0, v[160:161]
	v_pk_mul_f32 v[118:119], v[118:119], v[164:165]
	v_pk_mul_f32 v[116:117], v[116:117], v[162:163]
	v_pk_mul_f32 v[114:115], v[114:115], v[124:125]
	v_lshl_add_u64 v[122:123], v[140:141], 1, v[122:123]
	v_lshl_add_u64 v[124:125], v[158:159], 2, s[56:57]
	v_cvt_pk_bf16_f32 v160, v116, v117
	v_cvt_pk_bf16_f32 v161, v118, v119
	v_cvt_pk_bf16_f32 v162, v112, v113
	v_cvt_pk_bf16_f32 v163, v114, v115
	v_mov_b64_e32 v[196:197], v[160:161]
	v_mov_b64_e32 v[198:199], v[162:163]
	s_cbranch_vccnz .LBB0_243
; __device__ __forceinline__ void st_bf16x8(bf16_t* p, const f32x4 a, const f32x4 b) { uint4 o; o.x = cvt_pk_bf16(a[0], a[1]); o.y = cvt_pk_bf16(a[2], a[3]); o.z = cvt_pk_bf16(b[0], b[1]); o.w = cvt_pk_bf16(b[2], b[3]); *(uint4*)p = o; }
;     __device__ __forceinline__ void row(const f32x4 (&a)[2][2], int row, int pn, int wc, int fq) const {
;     ...
;             for (int bj = 0; bj < 2; ++bj) { const int d = head * 64 + bj * 32 + 8 * fq;
;                 const f32x4 v0 = g[bj][0] * rs * *(const f32x4*)(g_v + d), v1 = g[bj][1] * rs * *(const f32x4*)(g_v + d + 4);
;                 st_bf16x8(pV + (size_t)row * 512 + d, v0, v1);
;                 if (row >= NP && row < NTOK) { float* o = out + O_VS + (size_t)(row - NP) * 512 + d; *(f32x4*)o = v0; *(f32x4*)(o + 4) = v1; } }
	v_lshl_add_u64 v[158:159], v[140:141], 2, v[124:125]
	v_lshl_add_u64 v[160:161], v[158:159], 0, s[70:71]
	v_add_co_u32_e32 v158, vcc, 0x2108000, v158
	s_nop 1
	v_addc_co_u32_e32 v159, vcc, 0, v159, vcc
	global_store_dwordx4 v[158:159], v[116:119], off
	global_store_dwordx4 v[160:161], v[112:115], off offset:16
.LBB0_243:
	v_mov_b64_e32 v[112:113], v[212:213]
	v_mov_b64_e32 v[114:115], v[214:215]
	s_nop 0
	v_mov_b64_e32 v[116:117], v[216:217]
	v_mov_b64_e32 v[118:119], v[218:219]
	v_mov_b32_e32 v135, v134
	v_mov_b32_e32 v158, v134
	v_mov_b32_e32 v159, v134
	v_pk_mul_f32 v[126:127], v[126:127], v[134:135]
	v_pk_mul_f32 v[128:129], v[128:129], v[158:159]
	v_pk_mul_f32 v[130:131], v[130:131], v[134:135]
	v_pk_mul_f32 v[132:133], v[132:133], v[158:159]
	s_and_b64 vcc, exec, s[0:1]
	v_pk_mul_f32 v[114:115], v[128:129], v[114:115]
	v_pk_mul_f32 v[112:113], v[126:127], v[112:113]
	v_pk_mul_f32 v[118:119], v[132:133], v[118:119]
	v_pk_mul_f32 v[116:117], v[130:131], v[116:117]
	v_cvt_pk_bf16_f32 v126, v112, v113
	v_cvt_pk_bf16_f32 v127, v114, v115
	v_cvt_pk_bf16_f32 v129, v118, v119
	s_nop 0
	v_cvt_pk_bf16_f32 v128, v116, v117
	s_mov_b64 s[100:101], vcc
	v_and_b32_e32 v222, 1, v120
	s_movk_i32 s32, 0xfc40
	v_mad_i64_i32 v[122:123], s[98:99], v222, s32, v[122:123]
	v_cmp_eq_u32_e32 vcc, 0, v222
	s_nop 1
	v_cndmask_b32_dpp v200, v126, v196, vcc quad_perm:[1,0,3,2] row_mask:0xf bank_mask:0xf
	v_cndmask_b32_dpp v201, v127, v197, vcc quad_perm:[1,0,3,2] row_mask:0xf bank_mask:0xf
	v_cndmask_b32_dpp v202, v128, v198, vcc quad_perm:[1,0,3,2] row_mask:0xf bank_mask:0xf
	v_cndmask_b32_dpp v203, v129, v199, vcc quad_perm:[1,0,3,2] row_mask:0xf bank_mask:0xf
	v_cmp_ne_u32_e32 vcc, 0, v222
	s_nop 1
	v_cndmask_b32_dpp v126, v196, v126, vcc quad_perm:[1,0,3,2] row_mask:0xf bank_mask:0xf
	v_cndmask_b32_dpp v127, v197, v127, vcc quad_perm:[1,0,3,2] row_mask:0xf bank_mask:0xf
	v_cndmask_b32_dpp v128, v198, v128, vcc quad_perm:[1,0,3,2] row_mask:0xf bank_mask:0xf
	v_cndmask_b32_dpp v129, v199, v129, vcc quad_perm:[1,0,3,2] row_mask:0xf bank_mask:0xf
	global_store_dwordx4 v[122:123], v[200:203], off
	global_store_dwordx4 v[122:123], v[126:129], off offset:1024
	s_mov_b64 vcc, s[100:101]
	s_cbranch_vccnz .LBB0_245
	v_lshl_add_u64 v[122:123], v[152:153], 2, v[124:125]
	v_lshl_add_u64 v[124:125], v[122:123], 0, s[70:71]
	v_add_co_u32_e32 v122, vcc, 0x2108000, v122
	s_nop 1
	v_addc_co_u32_e32 v123, vcc, 0, v123, vcc
	global_store_dwordx4 v[122:123], v[112:115], off
	global_store_dwordx4 v[124:125], v[116:119], off offset:16

; __device__ __forceinline__ float gelu_tanh(float x) { const float u = 1.5957691216f * (x + 0.044715f * x * x * x); return x * __builtin_amdgcn_rcpf(1.f + __expf(-u)); }
; __device__ __forceinline__ void st_bf16x8(bf16_t* p, const f32x4 a, const f32x4 b) { uint4 o; o.x = cvt_pk_bf16(a[0], a[1]); o.y = cvt_pk_bf16(a[2], a[3]); o.z = cvt_pk_bf16(b[0], b[1]); o.w = cvt_pk_bf16(b[2], b[3]); *(uint4*)p = o; }
;     __device__ __forceinline__ void row(const f32x4 (&a)[2][2], int row, int pn, int wc, int fq) const {
;     ...
;             const int head = (pn - 2) * 4 + wc;
;             f32x4 g[2][2]; float ss = 0.f;
; #pragma unroll
;             for (int bj = 0; bj < 2; ++bj)
; #pragma unroll
;                 for (int n = 0; n < 2; ++n)
; #pragma unroll
;                     for (int j = 0; j < 4; ++j) { const float t = gelu_tanh(a[bj][n][j]); g[bj][n][j] = t; ss += t * t; }
;             ss += __shfl_xor(ss, 16); ss += __shfl_xor(ss, 32);
;             const float rs = rsqrtf(ss * (1.f / 64.f) + EPS);
; #pragma unroll
;             for (int bj = 0; bj < 2; ++bj) { const int d = head * 64 + bj * 32 + 8 * fq;
;                 const f32x4 v0 = g[bj][0] * rs * *(const f32x4*)(g_v + d), v1 = g[bj][1] * rs * *(const f32x4*)(g_v + d + 4);
;                 st_bf16x8(pV + (size_t)row * 512 + d, v0, v1);
.LBB0_255:
	s_andn2_b64 vcc, exec, s[0:1]
	s_cbranch_vccnz .LBB0_260
	v_mov_b32_e32 v190, 0x3d372713
	v_mov_b32_e32 v192, 0xbfcc422a
	v_mov_b32_e32 v194, 0x3fb8aa3b
	v_pk_mul_f32 v[96:97], v[92:93], v[190:191] op_sel_hi:[1,0]
	v_pk_mul_f32 v[100:101], v[94:95], v[190:191] op_sel_hi:[1,0]
	v_pk_mul_f32 v[106:107], v[88:89], v[190:191] op_sel_hi:[1,0]
	v_pk_mul_f32 v[108:109], v[90:91], v[190:191] op_sel_hi:[1,0]
	v_pk_mul_f32 v[110:111], v[84:85], v[190:191] op_sel_hi:[1,0]
	v_pk_mul_f32 v[112:113], v[86:87], v[190:191] op_sel_hi:[1,0]
	v_pk_mul_f32 v[114:115], v[80:81], v[190:191] op_sel_hi:[1,0]
	v_pk_mul_f32 v[116:117], v[82:83], v[190:191] op_sel_hi:[1,0]
	v_pk_mul_f32 v[96:97], v[92:93], v[96:97]
	v_pk_mul_f32 v[100:101], v[94:95], v[100:101]
	v_pk_mul_f32 v[106:107], v[88:89], v[106:107]
	v_pk_mul_f32 v[108:109], v[90:91], v[108:109]
	v_pk_mul_f32 v[110:111], v[84:85], v[110:111]
	v_pk_mul_f32 v[112:113], v[86:87], v[112:113]
	v_pk_mul_f32 v[114:115], v[80:81], v[114:115]
	v_pk_mul_f32 v[116:117], v[82:83], v[116:117]
	v_pk_fma_f32 v[96:97], v[92:93], v[96:97], v[92:93]
	v_pk_fma_f32 v[100:101], v[94:95], v[100:101], v[94:95]
	v_pk_fma_f32 v[106:107], v[88:89], v[106:107], v[88:89]
	v_pk_fma_f32 v[108:109], v[90:91], v[108:109], v[90:91]
	v_pk_fma_f32 v[110:111], v[84:85], v[110:111], v[84:85]
	v_pk_fma_f32 v[112:113], v[86:87], v[112:113], v[86:87]
	v_pk_fma_f32 v[114:115], v[80:81], v[114:115], v[80:81]
	v_pk_fma_f32 v[116:117], v[82:83], v[116:117], v[82:83]
	v_pk_mul_f32 v[96:97], v[96:97], v[192:193] op_sel_hi:[1,0]
	v_pk_mul_f32 v[100:101], v[100:101], v[192:193] op_sel_hi:[1,0]
	v_pk_mul_f32 v[106:107], v[106:107], v[192:193] op_sel_hi:[1,0]
	v_pk_mul_f32 v[108:109], v[108:109], v[192:193] op_sel_hi:[1,0]
	v_pk_mul_f32 v[110:111], v[110:111], v[192:193] op_sel_hi:[1,0]
	v_pk_mul_f32 v[112:113], v[112:113], v[192:193] op_sel_hi:[1,0]
	v_pk_mul_f32 v[114:115], v[114:115], v[192:193] op_sel_hi:[1,0]
	v_pk_mul_f32 v[116:117], v[116:117], v[192:193] op_sel_hi:[1,0]
	v_pk_mul_f32 v[96:97], v[96:97], v[194:195] op_sel_hi:[1,0]
	v_pk_mul_f32 v[100:101], v[100:101], v[194:195] op_sel_hi:[1,0]
	v_pk_mul_f32 v[106:107], v[106:107], v[194:195] op_sel_hi:[1,0]
	v_pk_mul_f32 v[108:109], v[108:109], v[194:195] op_sel_hi:[1,0]
	v_pk_mul_f32 v[110:111], v[110:111], v[194:195] op_sel_hi:[1,0]
	v_pk_mul_f32 v[112:113], v[112:113], v[194:195] op_sel_hi:[1,0]
	v_pk_mul_f32 v[114:115], v[114:115], v[194:195] op_sel_hi:[1,0]
	v_pk_mul_f32 v[116:117], v[116:117], v[194:195] op_sel_hi:[1,0]
	v_exp_f32_e32 v96, v96
	v_exp_f32_e32 v97, v97
	v_exp_f32_e32 v100, v100
	v_exp_f32_e32 v101, v101
	v_exp_f32_e32 v106, v106
	v_exp_f32_e32 v107, v107
	v_exp_f32_e32 v108, v108
	v_exp_f32_e32 v109, v109
	v_exp_f32_e32 v110, v110
	v_exp_f32_e32 v111, v111
	v_exp_f32_e32 v112, v112
	v_exp_f32_e32 v113, v113
	v_exp_f32_e32 v114, v114
	v_exp_f32_e32 v115, v115
	v_exp_f32_e32 v116, v116
	v_exp_f32_e32 v117, v117
	v_pk_add_f32 v[96:97], v[96:97], 1.0 op_sel_hi:[1,0]
	v_pk_add_f32 v[100:101], v[100:101], 1.0 op_sel_hi:[1,0]
	v_pk_add_f32 v[106:107], v[106:107], 1.0 op_sel_hi:[1,0]
	v_pk_add_f32 v[108:109], v[108:109], 1.0 op_sel_hi:[1,0]
	v_pk_add_f32 v[110:111], v[110:111], 1.0 op_sel_hi:[1,0]
	v_pk_add_f32 v[112:113], v[112:113], 1.0 op_sel_hi:[1,0]
	v_pk_add_f32 v[114:115], v[114:115], 1.0 op_sel_hi:[1,0]
	v_pk_add_f32 v[116:117], v[116:117], 1.0 op_sel_hi:[1,0]
	v_rcp_f32_e32 v96, v96
	v_rcp_f32_e32 v97, v97
	v_rcp_f32_e32 v100, v100
	v_rcp_f32_e32 v101, v101
	v_rcp_f32_e32 v106, v106
	v_rcp_f32_e32 v107, v107
	v_rcp_f32_e32 v108, v108
	v_rcp_f32_e32 v109, v109
	v_rcp_f32_e32 v110, v110
	v_rcp_f32_e32 v111, v111
	v_rcp_f32_e32 v112, v112
	v_rcp_f32_e32 v113, v113
	v_rcp_f32_e32 v114, v114
	v_rcp_f32_e32 v115, v115
	v_rcp_f32_e32 v116, v116
	v_rcp_f32_e32 v117, v117
	v_pk_mul_f32 v[96:97], v[92:93], v[96:97]
	v_pk_mul_f32 v[100:101], v[94:95], v[100:101]
	v_pk_mul_f32 v[106:107], v[88:89], v[106:107]
	v_pk_mul_f32 v[108:109], v[90:91], v[108:109]
	v_pk_mul_f32 v[110:111], v[84:85], v[110:111]
	v_pk_mul_f32 v[112:113], v[86:87], v[112:113]
	v_pk_mul_f32 v[114:115], v[80:81], v[114:115]
	v_pk_mul_f32 v[116:117], v[82:83], v[116:117]
	v_pk_mul_f32 v[98:99], v[96:97], v[96:97]
	v_pk_mul_f32 v[102:103], v[100:101], v[100:101]
	v_add_f32_e32 v98, v98, v99
	v_add_f32_e32 v98, v102, v98
	v_pk_mul_f32 v[118:119], v[106:107], v[106:107]
	v_add_f32_e32 v98, v103, v98
	v_add_f32_e32 v98, v118, v98
	v_pk_mul_f32 v[120:121], v[108:109], v[108:109]
	v_add_f32_e32 v98, v119, v98
	v_add_f32_e32 v98, v120, v98
	v_pk_mul_f32 v[122:123], v[110:111], v[110:111]
	v_add_f32_e32 v98, v121, v98
	v_add_f32_e32 v98, v98, v122
	v_pk_mul_f32 v[124:125], v[112:113], v[112:113]
	v_add_f32_e32 v98, v123, v98
	v_add_f32_e32 v98, v124, v98
	v_pk_mul_f32 v[126:127], v[114:115], v[114:115]
	v_add_f32_e32 v98, v125, v98
	v_add_f32_e32 v98, v126, v98
	v_pk_mul_f32 v[128:129], v[116:117], v[116:117]
	v_add_f32_e32 v98, v127, v98
	v_add_f32_e32 v98, v128, v98
	v_add_f32_e32 v98, v129, v98
	ds_bpermute_b32 v99, v229, v98
	v_lshl_add_u64 v[128:129], v[140:141], 2, s[18:19]
	v_ashrrev_i32_e32 v105, 31, v104
	v_lshlrev_b64 v[122:123], 10, v[104:105]
	v_lshlrev_b32_e32 v120, 9, v104
	s_waitcnt lgkmcnt(0)
	v_add_f32_e32 v98, v98, v99
	ds_bpermute_b32 v99, v230, v98
	v_mov_b32_e32 v121, v141
	v_cndmask_b32_e64 v105, 0, 1, s[10:11]
	v_cmp_ne_u32_e64 s[0:1], 1, v105
	s_waitcnt lgkmcnt(0)
	v_add_f32_e32 v98, v98, v99
	v_fmamk_f32 v98, v98, 0x3c800000, v188
	v_cmp_gt_f32_e32 vcc, s13, v98
	v_mul_f32_e32 v99, 0x4b800000, v98
	s_nop 0
	v_cndmask_b32_e32 v98, v98, v99, vcc
	v_rsq_f32_e32 v98, v98
	s_nop 0
	v_mul_f32_e32 v99, 0x45800000, v98
	v_cndmask_b32_e32 v118, v98, v99, vcc
	v_pk_mul_f32 v[124:125], v[96:97], v[118:119] op_sel_hi:[1,0]
	v_pk_mul_f32 v[126:127], v[100:101], v[118:119] op_sel_hi:[1,0]
	v_mov_b64_e32 v[96:97], v[208:209]
	v_mov_b64_e32 v[98:99], v[210:211]
	v_mov_b64_e32 v[100:101], v[204:205]
	v_mov_b64_e32 v[102:103], v[206:207]
	v_pk_mul_f32 v[106:107], v[106:107], v[118:119] op_sel_hi:[1,0]
	v_pk_mul_f32 v[108:109], v[108:109], v[118:119] op_sel_hi:[1,0]
	s_andn2_b64 vcc, exec, s[10:11]
	v_pk_mul_f32 v[96:97], v[96:97], v[106:107]
	v_lshl_add_u64 v[106:107], s[46:47], 0, v[122:123]
	v_pk_mul_f32 v[102:103], v[102:103], v[126:127]
	v_pk_mul_f32 v[100:101], v[100:101], v[124:125]
	v_pk_mul_f32 v[98:99], v[98:99], v[108:109]
	v_lshl_add_u64 v[106:107], v[140:141], 1, v[106:107]
	v_lshl_add_u64 v[108:109], v[120:121], 2, s[56:57]
	v_cvt_pk_bf16_f32 v122, v100, v101
	v_cvt_pk_bf16_f32 v123, v102, v103
	v_cvt_pk_bf16_f32 v124, v96, v97
	v_cvt_pk_bf16_f32 v125, v98, v99
	v_mov_b64_e32 v[196:197], v[122:123]
	v_mov_b64_e32 v[198:199], v[124:125]
	s_cbranch_vccnz .LBB0_258
	v_lshl_add_u64 v[120:121], v[140:141], 2, v[108:109]
	v_lshl_add_u64 v[122:123], v[120:121], 0, s[70:71]
	v_add_co_u32_e32 v120, vcc, 0x2108000, v120
	s_nop 1
	v_addc_co_u32_e32 v121, vcc, 0, v121, vcc
	global_store_dwordx4 v[120:121], v[100:103], off
	global_store_dwordx4 v[122:123], v[96:99], off offset:16
; __device__ __forceinline__ void st_bf16x8(bf16_t* p, const f32x4 a, const f32x4 b) { uint4 o; o.x = cvt_pk_bf16(a[0], a[1]); o.y = cvt_pk_bf16(a[2], a[3]); o.z = cvt_pk_bf16(b[0], b[1]); o.w = cvt_pk_bf16(b[2], b[3]); *(uint4*)p = o; }
;     __device__ __forceinline__ void row(const f32x4 (&a)[2][2], int row, int pn, int wc, int fq) const {
;     ...
;             for (int bj = 0; bj < 2; ++bj) { const int d = head * 64 + bj * 32 + 8 * fq;
;                 const f32x4 v0 = g[bj][0] * rs * *(const f32x4*)(g_v + d), v1 = g[bj][1] * rs * *(const f32x4*)(g_v + d + 4);
;                 st_bf16x8(pV + (size_t)row * 512 + d, v0, v1);
;                 if (row >= NP && row < NTOK) { float* o = out + O_VS + (size_t)(row - NP) * 512 + d; *(f32x4*)o = v0; *(f32x4*)(o + 4) = v1; } }
.LBB0_258:
	v_mov_b64_e32 v[96:97], v[212:213]
	v_mov_b64_e32 v[98:99], v[214:215]
	s_nop 0
	v_mov_b64_e32 v[100:101], v[216:217]
	v_mov_b64_e32 v[102:103], v[218:219]
	v_mov_b32_e32 v119, v118
	v_mov_b32_e32 v120, v118
	v_mov_b32_e32 v121, v118
	v_pk_mul_f32 v[110:111], v[110:111], v[118:119]
	v_pk_mul_f32 v[112:113], v[112:113], v[120:121]
	v_pk_mul_f32 v[114:115], v[114:115], v[118:119]
	v_pk_mul_f32 v[116:117], v[116:117], v[120:121]
	s_and_b64 vcc, exec, s[0:1]
	v_pk_mul_f32 v[98:99], v[112:113], v[98:99]
	v_pk_mul_f32 v[96:97], v[110:111], v[96:97]
	v_pk_mul_f32 v[102:103], v[116:117], v[102:103]
	v_pk_mul_f32 v[100:101], v[114:115], v[100:101]
	v_cvt_pk_bf16_f32 v110, v96, v97
	v_cvt_pk_bf16_f32 v111, v98, v99
	v_cvt_pk_bf16_f32 v113, v102, v103
	s_nop 0
	v_cvt_pk_bf16_f32 v112, v100, v101
	s_mov_b64 s[100:101], vcc
	v_and_b32_e32 v222, 1, v104
	s_movk_i32 s32, 0xfc40
	v_mad_i64_i32 v[106:107], s[98:99], v222, s32, v[106:107]
	v_cmp_eq_u32_e32 vcc, 0, v222
	s_nop 1
	v_cndmask_b32_dpp v200, v110, v196, vcc quad_perm:[1,0,3,2] row_mask:0xf bank_mask:0xf
	v_cndmask_b32_dpp v201, v111, v197, vcc quad_perm:[1,0,3,2] row_mask:0xf bank_mask:0xf
	v_cndmask_b32_dpp v202, v112, v198, vcc quad_perm:[1,0,3,2] row_mask:0xf bank_mask:0xf
	v_cndmask_b32_dpp v203, v113, v199, vcc quad_perm:[1,0,3,2] row_mask:0xf bank_mask:0xf
	v_cmp_ne_u32_e32 vcc, 0, v222
	s_nop 1
	v_cndmask_b32_dpp v110, v196, v110, vcc quad_perm:[1,0,3,2] row_mask:0xf bank_mask:0xf
	v_cndmask_b32_dpp v111, v197, v111, vcc quad_perm:[1,0,3,2] row_mask:0xf bank_mask:0xf
	v_cndmask_b32_dpp v112, v198, v112, vcc quad_perm:[1,0,3,2] row_mask:0xf bank_mask:0xf
	v_cndmask_b32_dpp v113, v199, v113, vcc quad_perm:[1,0,3,2] row_mask:0xf bank_mask:0xf
	global_store_dwordx4 v[106:107], v[200:203], off
	global_store_dwordx4 v[106:107], v[110:113], off offset:1024
	s_mov_b64 vcc, s[100:101]
	s_cbranch_vccnz .LBB0_260
	v_lshl_add_u64 v[106:107], v[152:153], 2, v[108:109]
	v_lshl_add_u64 v[108:109], v[106:107], 0, s[70:71]
	v_add_co_u32_e32 v106, vcc, 0x2108000, v106
	s_nop 1
	v_addc_co_u32_e32 v107, vcc, 0, v107, vcc
	global_store_dwordx4 v[106:107], v[96:99], off
	global_store_dwordx4 v[108:109], v[100:103], off offset:16

; __device__ __forceinline__ float gelu_tanh(float x) { const float u = 1.5957691216f * (x + 0.044715f * x * x * x); return x * __builtin_amdgcn_rcpf(1.f + __expf(-u)); }
; __device__ __forceinline__ void st_bf16x8(bf16_t* p, const f32x4 a, const f32x4 b) { uint4 o; o.x = cvt_pk_bf16(a[0], a[1]); o.y = cvt_pk_bf16(a[2], a[3]); o.z = cvt_pk_bf16(b[0], b[1]); o.w = cvt_pk_bf16(b[2], b[3]); *(uint4*)p = o; }
;     __device__ __forceinline__ void row(const f32x4 (&a)[2][2], int row, int pn, int wc, int fq) const {
;     ...
;             const int head = (pn - 2) * 4 + wc;
;             f32x4 g[2][2]; float ss = 0.f;
; #pragma unroll
;             for (int bj = 0; bj < 2; ++bj)
; #pragma unroll
;                 for (int n = 0; n < 2; ++n)
; #pragma unroll
;                     for (int j = 0; j < 4; ++j) { const float t = gelu_tanh(a[bj][n][j]); g[bj][n][j] = t; ss += t * t; }
;             ss += __shfl_xor(ss, 16); ss += __shfl_xor(ss, 32);
;             const float rs = rsqrtf(ss * (1.f / 64.f) + EPS);
; #pragma unroll
;             for (int bj = 0; bj < 2; ++bj) { const int d = head * 64 + bj * 32 + 8 * fq;
;                 const f32x4 v0 = g[bj][0] * rs * *(const f32x4*)(g_v + d), v1 = g[bj][1] * rs * *(const f32x4*)(g_v + d + 4);
;                 st_bf16x8(pV + (size_t)row * 512 + d, v0, v1);
.LBB0_272:
	s_and_b64 vcc, exec, s[0:1]
	s_cbranch_vccz .LBB0_277
	v_mov_b32_e32 v190, 0x3d372713
	v_mov_b32_e32 v192, 0xbfcc422a
	v_mov_b32_e32 v194, 0x3fb8aa3b
	v_pk_mul_f32 v[80:81], v[76:77], v[190:191] op_sel_hi:[1,0]
	v_pk_mul_f32 v[84:85], v[78:79], v[190:191] op_sel_hi:[1,0]
	v_pk_mul_f32 v[90:91], v[72:73], v[190:191] op_sel_hi:[1,0]
	v_pk_mul_f32 v[92:93], v[74:75], v[190:191] op_sel_hi:[1,0]
	v_pk_mul_f32 v[94:95], v[68:69], v[190:191] op_sel_hi:[1,0]
	v_pk_mul_f32 v[96:97], v[70:71], v[190:191] op_sel_hi:[1,0]
	v_pk_mul_f32 v[98:99], v[64:65], v[190:191] op_sel_hi:[1,0]
	v_pk_mul_f32 v[100:101], v[66:67], v[190:191] op_sel_hi:[1,0]
	v_pk_mul_f32 v[80:81], v[76:77], v[80:81]
	v_pk_mul_f32 v[84:85], v[78:79], v[84:85]
	v_pk_mul_f32 v[90:91], v[72:73], v[90:91]
	v_pk_mul_f32 v[92:93], v[74:75], v[92:93]
	v_pk_mul_f32 v[94:95], v[68:69], v[94:95]
	v_pk_mul_f32 v[96:97], v[70:71], v[96:97]
	v_pk_mul_f32 v[98:99], v[64:65], v[98:99]
	v_pk_mul_f32 v[100:101], v[66:67], v[100:101]
	v_pk_fma_f32 v[80:81], v[76:77], v[80:81], v[76:77]
	v_pk_fma_f32 v[84:85], v[78:79], v[84:85], v[78:79]
	v_pk_fma_f32 v[90:91], v[72:73], v[90:91], v[72:73]
	v_pk_fma_f32 v[92:93], v[74:75], v[92:93], v[74:75]
	v_pk_fma_f32 v[94:95], v[68:69], v[94:95], v[68:69]
	v_pk_fma_f32 v[96:97], v[70:71], v[96:97], v[70:71]
	v_pk_fma_f32 v[98:99], v[64:65], v[98:99], v[64:65]
	v_pk_fma_f32 v[100:101], v[66:67], v[100:101], v[66:67]
	v_pk_mul_f32 v[80:81], v[80:81], v[192:193] op_sel_hi:[1,0]
	v_pk_mul_f32 v[84:85], v[84:85], v[192:193] op_sel_hi:[1,0]
	v_pk_mul_f32 v[90:91], v[90:91], v[192:193] op_sel_hi:[1,0]
	v_pk_mul_f32 v[92:93], v[92:93], v[192:193] op_sel_hi:[1,0]
	v_pk_mul_f32 v[94:95], v[94:95], v[192:193] op_sel_hi:[1,0]
	v_pk_mul_f32 v[96:97], v[96:97], v[192:193] op_sel_hi:[1,0]
	v_pk_mul_f32 v[98:99], v[98:99], v[192:193] op_sel_hi:[1,0]
	v_pk_mul_f32 v[100:101], v[100:101], v[192:193] op_sel_hi:[1,0]
	v_pk_mul_f32 v[80:81], v[80:81], v[194:195] op_sel_hi:[1,0]
	v_pk_mul_f32 v[84:85], v[84:85], v[194:195] op_sel_hi:[1,0]
	v_pk_mul_f32 v[90:91], v[90:91], v[194:195] op_sel_hi:[1,0]
	v_pk_mul_f32 v[92:93], v[92:93], v[194:195] op_sel_hi:[1,0]
	v_pk_mul_f32 v[94:95], v[94:95], v[194:195] op_sel_hi:[1,0]
	v_pk_mul_f32 v[96:97], v[96:97], v[194:195] op_sel_hi:[1,0]
	v_pk_mul_f32 v[98:99], v[98:99], v[194:195] op_sel_hi:[1,0]
	v_pk_mul_f32 v[100:101], v[100:101], v[194:195] op_sel_hi:[1,0]
	v_exp_f32_e32 v80, v80
	v_exp_f32_e32 v81, v81
	v_exp_f32_e32 v84, v84
	v_exp_f32_e32 v85, v85
	v_exp_f32_e32 v90, v90
	v_exp_f32_e32 v91, v91
	v_exp_f32_e32 v92, v92
	v_exp_f32_e32 v93, v93
	v_exp_f32_e32 v94, v94
	v_exp_f32_e32 v95, v95
	v_exp_f32_e32 v96, v96
	v_exp_f32_e32 v97, v97
	v_exp_f32_e32 v98, v98
	v_exp_f32_e32 v99, v99
	v_exp_f32_e32 v100, v100
	v_exp_f32_e32 v101, v101
	v_pk_add_f32 v[80:81], v[80:81], 1.0 op_sel_hi:[1,0]
	v_pk_add_f32 v[84:85], v[84:85], 1.0 op_sel_hi:[1,0]
	v_pk_add_f32 v[90:91], v[90:91], 1.0 op_sel_hi:[1,0]
	v_pk_add_f32 v[92:93], v[92:93], 1.0 op_sel_hi:[1,0]
	v_pk_add_f32 v[94:95], v[94:95], 1.0 op_sel_hi:[1,0]
	v_pk_add_f32 v[96:97], v[96:97], 1.0 op_sel_hi:[1,0]
	v_pk_add_f32 v[98:99], v[98:99], 1.0 op_sel_hi:[1,0]
	v_pk_add_f32 v[100:101], v[100:101], 1.0 op_sel_hi:[1,0]
	v_rcp_f32_e32 v80, v80
	v_rcp_f32_e32 v81, v81
	v_rcp_f32_e32 v84, v84
	v_rcp_f32_e32 v85, v85
	v_rcp_f32_e32 v90, v90
	v_rcp_f32_e32 v91, v91
	v_rcp_f32_e32 v92, v92
	v_rcp_f32_e32 v93, v93
	v_rcp_f32_e32 v94, v94
	v_rcp_f32_e32 v95, v95
	v_rcp_f32_e32 v96, v96
	v_rcp_f32_e32 v97, v97
	v_rcp_f32_e32 v98, v98
	v_rcp_f32_e32 v99, v99
	v_rcp_f32_e32 v100, v100
	v_rcp_f32_e32 v101, v101
	v_pk_mul_f32 v[80:81], v[76:77], v[80:81]
	v_pk_mul_f32 v[84:85], v[78:79], v[84:85]
	v_pk_mul_f32 v[90:91], v[72:73], v[90:91]
	v_pk_mul_f32 v[92:93], v[74:75], v[92:93]
	v_pk_mul_f32 v[94:95], v[68:69], v[94:95]
	v_pk_mul_f32 v[96:97], v[70:71], v[96:97]
	v_pk_mul_f32 v[98:99], v[64:65], v[98:99]
	v_pk_mul_f32 v[100:101], v[66:67], v[100:101]
	v_pk_mul_f32 v[82:83], v[80:81], v[80:81]
	v_pk_mul_f32 v[86:87], v[84:85], v[84:85]
	v_add_f32_e32 v82, v82, v83
	v_add_f32_e32 v82, v86, v82
	v_pk_mul_f32 v[102:103], v[90:91], v[90:91]
	v_add_f32_e32 v82, v87, v82
	v_add_f32_e32 v82, v102, v82
	v_pk_mul_f32 v[104:105], v[92:93], v[92:93]
	v_add_f32_e32 v82, v103, v82
	v_add_f32_e32 v82, v104, v82
	v_pk_mul_f32 v[106:107], v[94:95], v[94:95]
	v_add_f32_e32 v82, v105, v82
	v_add_f32_e32 v82, v82, v106
	v_pk_mul_f32 v[108:109], v[96:97], v[96:97]
	v_add_f32_e32 v82, v107, v82
	v_add_f32_e32 v82, v108, v82
	v_pk_mul_f32 v[110:111], v[98:99], v[98:99]
	v_add_f32_e32 v82, v109, v82
	v_add_f32_e32 v82, v110, v82
	v_pk_mul_f32 v[112:113], v[100:101], v[100:101]
	v_add_f32_e32 v82, v111, v82
	v_add_f32_e32 v82, v112, v82
	v_add_f32_e32 v82, v113, v82
	ds_bpermute_b32 v83, v229, v82
	v_lshl_add_u64 v[112:113], v[140:141], 2, s[18:19]
	v_ashrrev_i32_e32 v89, 31, v88
	v_lshlrev_b64 v[106:107], 10, v[88:89]
	v_lshlrev_b32_e32 v104, 9, v88
	s_waitcnt lgkmcnt(0)
	v_add_f32_e32 v82, v82, v83
	ds_bpermute_b32 v83, v230, v82
	v_mov_b32_e32 v105, v141
	v_cndmask_b32_e64 v89, 0, 1, s[10:11]
	v_cmp_ne_u32_e64 s[0:1], 1, v89
	s_waitcnt lgkmcnt(0)
	v_add_f32_e32 v82, v82, v83
	v_fmamk_f32 v82, v82, 0x3c800000, v188
	v_cmp_gt_f32_e32 vcc, s13, v82
	v_mul_f32_e32 v83, 0x4b800000, v82
	s_nop 0
	v_cndmask_b32_e32 v82, v82, v83, vcc
	v_rsq_f32_e32 v82, v82
	s_nop 0
	v_mul_f32_e32 v83, 0x45800000, v82
	v_cndmask_b32_e32 v102, v82, v83, vcc
	v_pk_mul_f32 v[108:109], v[80:81], v[102:103] op_sel_hi:[1,0]
	v_pk_mul_f32 v[110:111], v[84:85], v[102:103] op_sel_hi:[1,0]
	v_mov_b64_e32 v[80:81], v[208:209]
	v_mov_b64_e32 v[82:83], v[210:211]
	v_mov_b64_e32 v[84:85], v[204:205]
	v_mov_b64_e32 v[86:87], v[206:207]
	v_pk_mul_f32 v[90:91], v[90:91], v[102:103] op_sel_hi:[1,0]
	v_pk_mul_f32 v[92:93], v[92:93], v[102:103] op_sel_hi:[1,0]
	s_andn2_b64 vcc, exec, s[10:11]
	v_pk_mul_f32 v[80:81], v[80:81], v[90:91]
	v_lshl_add_u64 v[90:91], s[46:47], 0, v[106:107]
	v_pk_mul_f32 v[86:87], v[86:87], v[110:111]
	v_pk_mul_f32 v[84:85], v[84:85], v[108:109]
	v_pk_mul_f32 v[82:83], v[82:83], v[92:93]
	v_lshl_add_u64 v[90:91], v[140:141], 1, v[90:91]
	v_lshl_add_u64 v[92:93], v[104:105], 2, s[56:57]
	v_cvt_pk_bf16_f32 v106, v84, v85
	v_cvt_pk_bf16_f32 v107, v86, v87
	v_cvt_pk_bf16_f32 v108, v80, v81
	v_cvt_pk_bf16_f32 v109, v82, v83
	v_mov_b64_e32 v[196:197], v[106:107]
	v_mov_b64_e32 v[198:199], v[108:109]
	s_cbranch_vccnz .LBB0_275
	v_lshl_add_u64 v[104:105], v[140:141], 2, v[92:93]
	v_lshl_add_u64 v[106:107], v[104:105], 0, s[70:71]
	v_add_co_u32_e32 v104, vcc, 0x2108000, v104
	s_nop 1
	v_addc_co_u32_e32 v105, vcc, 0, v105, vcc
	global_store_dwordx4 v[104:105], v[84:87], off
	global_store_dwordx4 v[106:107], v[80:83], off offset:16
; __device__ __forceinline__ void st_bf16x8(bf16_t* p, const f32x4 a, const f32x4 b) { uint4 o; o.x = cvt_pk_bf16(a[0], a[1]); o.y = cvt_pk_bf16(a[2], a[3]); o.z = cvt_pk_bf16(b[0], b[1]); o.w = cvt_pk_bf16(b[2], b[3]); *(uint4*)p = o; }
;     __device__ __forceinline__ void row(const f32x4 (&a)[2][2], int row, int pn, int wc, int fq) const {
;     ...
;             for (int bj = 0; bj < 2; ++bj) { const int d = head * 64 + bj * 32 + 8 * fq;
;                 const f32x4 v0 = g[bj][0] * rs * *(const f32x4*)(g_v + d), v1 = g[bj][1] * rs * *(const f32x4*)(g_v + d + 4);
;                 st_bf16x8(pV + (size_t)row * 512 + d, v0, v1);
;                 if (row >= NP && row < NTOK) { float* o = out + O_VS + (size_t)(row - NP) * 512 + d; *(f32x4*)o = v0; *(f32x4*)(o + 4) = v1; } }
.LBB0_275:
	v_mov_b64_e32 v[80:81], v[212:213]
	v_mov_b64_e32 v[82:83], v[214:215]
	s_nop 0
	v_mov_b64_e32 v[84:85], v[216:217]
	v_mov_b64_e32 v[86:87], v[218:219]
	v_mov_b32_e32 v103, v102
	v_mov_b32_e32 v104, v102
	v_mov_b32_e32 v105, v102
	v_pk_mul_f32 v[94:95], v[94:95], v[102:103]
	v_pk_mul_f32 v[96:97], v[96:97], v[104:105]
	v_pk_mul_f32 v[98:99], v[98:99], v[102:103]
	v_pk_mul_f32 v[100:101], v[100:101], v[104:105]
	s_and_b64 vcc, exec, s[0:1]
	v_pk_mul_f32 v[82:83], v[96:97], v[82:83]
	v_pk_mul_f32 v[80:81], v[94:95], v[80:81]
	v_pk_mul_f32 v[86:87], v[100:101], v[86:87]
	v_pk_mul_f32 v[84:85], v[98:99], v[84:85]
	v_cvt_pk_bf16_f32 v94, v80, v81
	v_cvt_pk_bf16_f32 v95, v82, v83
	v_cvt_pk_bf16_f32 v97, v86, v87
	s_nop 0
	v_cvt_pk_bf16_f32 v96, v84, v85
	s_mov_b64 s[100:101], vcc
	v_and_b32_e32 v222, 1, v88
	s_movk_i32 s32, 0xfc40
	v_mad_i64_i32 v[90:91], s[98:99], v222, s32, v[90:91]
	v_cmp_eq_u32_e32 vcc, 0, v222
	s_nop 1
	v_cndmask_b32_dpp v200, v94, v196, vcc quad_perm:[1,0,3,2] row_mask:0xf bank_mask:0xf
	v_cndmask_b32_dpp v201, v95, v197, vcc quad_perm:[1,0,3,2] row_mask:0xf bank_mask:0xf
	v_cndmask_b32_dpp v202, v96, v198, vcc quad_perm:[1,0,3,2] row_mask:0xf bank_mask:0xf
	v_cndmask_b32_dpp v203, v97, v199, vcc quad_perm:[1,0,3,2] row_mask:0xf bank_mask:0xf
	v_cmp_ne_u32_e32 vcc, 0, v222
	s_nop 1
	v_cndmask_b32_dpp v94, v196, v94, vcc quad_perm:[1,0,3,2] row_mask:0xf bank_mask:0xf
	v_cndmask_b32_dpp v95, v197, v95, vcc quad_perm:[1,0,3,2] row_mask:0xf bank_mask:0xf
	v_cndmask_b32_dpp v96, v198, v96, vcc quad_perm:[1,0,3,2] row_mask:0xf bank_mask:0xf
	v_cndmask_b32_dpp v97, v199, v97, vcc quad_perm:[1,0,3,2] row_mask:0xf bank_mask:0xf
	global_store_dwordx4 v[90:91], v[200:203], off
	global_store_dwordx4 v[90:91], v[94:97], off offset:1024
	s_mov_b64 vcc, s[100:101]
	s_cbranch_vccnz .LBB0_277
	v_lshl_add_u64 v[90:91], v[152:153], 2, v[92:93]
	v_lshl_add_u64 v[92:93], v[90:91], 0, s[70:71]
	v_add_co_u32_e32 v90, vcc, 0x2108000, v90
	s_nop 1
	v_addc_co_u32_e32 v91, vcc, 0, v91, vcc
	global_store_dwordx4 v[90:91], v[80:83], off
	global_store_dwordx4 v[92:93], v[84:87], off offset:16

; __device__ __forceinline__ float gelu_tanh(float x) { const float u = 1.5957691216f * (x + 0.044715f * x * x * x); return x * __builtin_amdgcn_rcpf(1.f + __expf(-u)); }
; __device__ __forceinline__ void st_bf16x8(bf16_t* p, const f32x4 a, const f32x4 b) { uint4 o; o.x = cvt_pk_bf16(a[0], a[1]); o.y = cvt_pk_bf16(a[2], a[3]); o.z = cvt_pk_bf16(b[0], b[1]); o.w = cvt_pk_bf16(b[2], b[3]); *(uint4*)p = o; }
;     __device__ __forceinline__ void row(const f32x4 (&a)[2][2], int row, int pn, int wc, int fq) const {
;     ...
;             const int head = (pn - 2) * 4 + wc;
;             f32x4 g[2][2]; float ss = 0.f;
; #pragma unroll
;             for (int bj = 0; bj < 2; ++bj)
; #pragma unroll
;                 for (int n = 0; n < 2; ++n)
; #pragma unroll
;                     for (int j = 0; j < 4; ++j) { const float t = gelu_tanh(a[bj][n][j]); g[bj][n][j] = t; ss += t * t; }
;             ss += __shfl_xor(ss, 16); ss += __shfl_xor(ss, 32);
;             const float rs = rsqrtf(ss * (1.f / 64.f) + EPS);
; #pragma unroll
;             for (int bj = 0; bj < 2; ++bj) { const int d = head * 64 + bj * 32 + 8 * fq;
;                 const f32x4 v0 = g[bj][0] * rs * *(const f32x4*)(g_v + d), v1 = g[bj][1] * rs * *(const f32x4*)(g_v + d + 4);
;                 st_bf16x8(pV + (size_t)row * 512 + d, v0, v1);
.LBB0_295:
	s_andn2_b64 vcc, exec, s[0:1]
	s_cbranch_vccnz .LBB0_301
	v_mov_b32_e32 v190, 0x3d372713
	v_mov_b32_e32 v192, 0xbfcc422a
	v_mov_b32_e32 v194, 0x3fb8aa3b
	v_pk_mul_f32 v[64:65], v[60:61], v[190:191] op_sel_hi:[1,0]
	v_pk_mul_f32 v[68:69], v[62:63], v[190:191] op_sel_hi:[1,0]
	v_pk_mul_f32 v[74:75], v[56:57], v[190:191] op_sel_hi:[1,0]
	v_pk_mul_f32 v[76:77], v[58:59], v[190:191] op_sel_hi:[1,0]
	v_pk_mul_f32 v[78:79], v[52:53], v[190:191] op_sel_hi:[1,0]
	v_pk_mul_f32 v[80:81], v[54:55], v[190:191] op_sel_hi:[1,0]
	v_pk_mul_f32 v[82:83], v[48:49], v[190:191] op_sel_hi:[1,0]
	v_pk_mul_f32 v[84:85], v[50:51], v[190:191] op_sel_hi:[1,0]
	v_pk_mul_f32 v[64:65], v[60:61], v[64:65]
	v_pk_mul_f32 v[68:69], v[62:63], v[68:69]
	v_pk_mul_f32 v[74:75], v[56:57], v[74:75]
	v_pk_mul_f32 v[76:77], v[58:59], v[76:77]
	v_pk_mul_f32 v[78:79], v[52:53], v[78:79]
	v_pk_mul_f32 v[80:81], v[54:55], v[80:81]
	v_pk_mul_f32 v[82:83], v[48:49], v[82:83]
	v_pk_mul_f32 v[84:85], v[50:51], v[84:85]
	v_pk_fma_f32 v[64:65], v[60:61], v[64:65], v[60:61]
	v_pk_fma_f32 v[68:69], v[62:63], v[68:69], v[62:63]
	v_pk_fma_f32 v[74:75], v[56:57], v[74:75], v[56:57]
	v_pk_fma_f32 v[76:77], v[58:59], v[76:77], v[58:59]
	v_pk_fma_f32 v[78:79], v[52:53], v[78:79], v[52:53]
	v_pk_fma_f32 v[80:81], v[54:55], v[80:81], v[54:55]
	v_pk_fma_f32 v[82:83], v[48:49], v[82:83], v[48:49]
	v_pk_fma_f32 v[84:85], v[50:51], v[84:85], v[50:51]
	v_pk_mul_f32 v[64:65], v[64:65], v[192:193] op_sel_hi:[1,0]
	v_pk_mul_f32 v[68:69], v[68:69], v[192:193] op_sel_hi:[1,0]
	v_pk_mul_f32 v[74:75], v[74:75], v[192:193] op_sel_hi:[1,0]
	v_pk_mul_f32 v[76:77], v[76:77], v[192:193] op_sel_hi:[1,0]
	v_pk_mul_f32 v[78:79], v[78:79], v[192:193] op_sel_hi:[1,0]
	v_pk_mul_f32 v[80:81], v[80:81], v[192:193] op_sel_hi:[1,0]
	v_pk_mul_f32 v[82:83], v[82:83], v[192:193] op_sel_hi:[1,0]
	v_pk_mul_f32 v[84:85], v[84:85], v[192:193] op_sel_hi:[1,0]
	v_pk_mul_f32 v[64:65], v[64:65], v[194:195] op_sel_hi:[1,0]
	v_pk_mul_f32 v[68:69], v[68:69], v[194:195] op_sel_hi:[1,0]
	v_pk_mul_f32 v[74:75], v[74:75], v[194:195] op_sel_hi:[1,0]
	v_pk_mul_f32 v[76:77], v[76:77], v[194:195] op_sel_hi:[1,0]
	v_pk_mul_f32 v[78:79], v[78:79], v[194:195] op_sel_hi:[1,0]
	v_pk_mul_f32 v[80:81], v[80:81], v[194:195] op_sel_hi:[1,0]
	v_pk_mul_f32 v[82:83], v[82:83], v[194:195] op_sel_hi:[1,0]
	v_pk_mul_f32 v[84:85], v[84:85], v[194:195] op_sel_hi:[1,0]
	v_exp_f32_e32 v64, v64
	v_exp_f32_e32 v65, v65
	v_exp_f32_e32 v68, v68
	v_exp_f32_e32 v69, v69
	v_exp_f32_e32 v74, v74
	v_exp_f32_e32 v75, v75
	v_exp_f32_e32 v76, v76
	v_exp_f32_e32 v77, v77
	v_exp_f32_e32 v78, v78
	v_exp_f32_e32 v79, v79
	v_exp_f32_e32 v80, v80
	v_exp_f32_e32 v81, v81
	v_exp_f32_e32 v82, v82
	v_exp_f32_e32 v83, v83
	v_exp_f32_e32 v84, v84
	v_exp_f32_e32 v85, v85
	v_pk_add_f32 v[64:65], v[64:65], 1.0 op_sel_hi:[1,0]
	v_pk_add_f32 v[68:69], v[68:69], 1.0 op_sel_hi:[1,0]
	v_pk_add_f32 v[74:75], v[74:75], 1.0 op_sel_hi:[1,0]
	v_pk_add_f32 v[76:77], v[76:77], 1.0 op_sel_hi:[1,0]
	v_pk_add_f32 v[78:79], v[78:79], 1.0 op_sel_hi:[1,0]
	v_pk_add_f32 v[80:81], v[80:81], 1.0 op_sel_hi:[1,0]
	v_pk_add_f32 v[82:83], v[82:83], 1.0 op_sel_hi:[1,0]
	v_pk_add_f32 v[84:85], v[84:85], 1.0 op_sel_hi:[1,0]
	v_rcp_f32_e32 v64, v64
	v_rcp_f32_e32 v65, v65
	v_rcp_f32_e32 v68, v68
	v_rcp_f32_e32 v69, v69
	v_rcp_f32_e32 v74, v74
	v_rcp_f32_e32 v75, v75
	v_rcp_f32_e32 v76, v76
	v_rcp_f32_e32 v77, v77
	v_rcp_f32_e32 v78, v78
	v_rcp_f32_e32 v79, v79
	v_rcp_f32_e32 v80, v80
	v_rcp_f32_e32 v81, v81
	v_rcp_f32_e32 v82, v82
	v_rcp_f32_e32 v83, v83
	v_rcp_f32_e32 v84, v84
	v_rcp_f32_e32 v85, v85
	v_pk_mul_f32 v[64:65], v[60:61], v[64:65]
	v_pk_mul_f32 v[68:69], v[62:63], v[68:69]
	v_pk_mul_f32 v[74:75], v[56:57], v[74:75]
	v_pk_mul_f32 v[76:77], v[58:59], v[76:77]
	v_pk_mul_f32 v[78:79], v[52:53], v[78:79]
	v_pk_mul_f32 v[80:81], v[54:55], v[80:81]
	v_pk_mul_f32 v[82:83], v[48:49], v[82:83]
	v_pk_mul_f32 v[84:85], v[50:51], v[84:85]
	v_pk_mul_f32 v[66:67], v[64:65], v[64:65]
	v_pk_mul_f32 v[70:71], v[68:69], v[68:69]
	v_add_f32_e32 v66, v66, v67
	v_add_f32_e32 v66, v70, v66
	v_pk_mul_f32 v[86:87], v[74:75], v[74:75]
	v_add_f32_e32 v66, v71, v66
	v_add_f32_e32 v66, v86, v66
	v_pk_mul_f32 v[88:89], v[76:77], v[76:77]
	v_add_f32_e32 v66, v87, v66
	v_add_f32_e32 v66, v88, v66
	v_pk_mul_f32 v[90:91], v[78:79], v[78:79]
	v_add_f32_e32 v66, v89, v66
	v_add_f32_e32 v66, v66, v90
	v_pk_mul_f32 v[92:93], v[80:81], v[80:81]
	v_add_f32_e32 v66, v91, v66
	v_add_f32_e32 v66, v92, v66
	v_pk_mul_f32 v[94:95], v[82:83], v[82:83]
	v_add_f32_e32 v66, v93, v66
	v_add_f32_e32 v66, v94, v66
	v_pk_mul_f32 v[96:97], v[84:85], v[84:85]
	v_add_f32_e32 v66, v95, v66
	v_add_f32_e32 v66, v96, v66
	v_add_f32_e32 v66, v97, v66
	ds_bpermute_b32 v67, v229, v66
	v_lshl_add_u64 v[96:97], v[140:141], 2, s[18:19]
	v_ashrrev_i32_e32 v73, 31, v72
	v_lshlrev_b64 v[90:91], 10, v[72:73]
	v_lshlrev_b32_e32 v88, 9, v72
	s_waitcnt lgkmcnt(0)
	v_add_f32_e32 v66, v66, v67
	ds_bpermute_b32 v67, v230, v66
	v_mov_b32_e32 v89, v141
	s_waitcnt lgkmcnt(0)
	v_add_f32_e32 v66, v66, v67
	v_fmamk_f32 v66, v66, 0x3c800000, v188
	v_cmp_gt_f32_e32 vcc, s13, v66
	v_mul_f32_e32 v67, 0x4b800000, v66
	s_nop 0
	v_cndmask_b32_e32 v66, v66, v67, vcc
	v_rsq_f32_e32 v66, v66
	s_nop 0
	v_mul_f32_e32 v67, 0x45800000, v66
	v_cndmask_b32_e32 v86, v66, v67, vcc
	v_pk_mul_f32 v[92:93], v[64:65], v[86:87] op_sel_hi:[1,0]
	v_pk_mul_f32 v[94:95], v[68:69], v[86:87] op_sel_hi:[1,0]
	v_mov_b64_e32 v[64:65], v[208:209]
	v_mov_b64_e32 v[66:67], v[210:211]
	v_mov_b64_e32 v[68:69], v[204:205]
	v_mov_b64_e32 v[70:71], v[206:207]
	v_pk_mul_f32 v[74:75], v[74:75], v[86:87] op_sel_hi:[1,0]
	v_pk_mul_f32 v[76:77], v[76:77], v[86:87] op_sel_hi:[1,0]
	v_pk_mul_f32 v[64:65], v[64:65], v[74:75]
	v_lshl_add_u64 v[74:75], s[46:47], 0, v[90:91]
	v_pk_mul_f32 v[70:71], v[70:71], v[94:95]
	v_pk_mul_f32 v[68:69], v[68:69], v[92:93]
	v_pk_mul_f32 v[66:67], v[66:67], v[76:77]
	v_lshl_add_u64 v[76:77], v[140:141], 1, v[74:75]
	v_lshl_add_u64 v[74:75], v[88:89], 2, s[56:57]
	v_cvt_pk_bf16_f32 v90, v68, v69
	v_cvt_pk_bf16_f32 v91, v70, v71
	v_cvt_pk_bf16_f32 v92, v64, v65
	v_cvt_pk_bf16_f32 v93, v66, v67
	v_mov_b64_e32 v[196:197], v[90:91]
	v_mov_b64_e32 v[198:199], v[92:93]
	s_and_saveexec_b64 s[0:1], s[10:11]
	s_cbranch_execz .LBB0_298
	v_lshl_add_u64 v[88:89], v[140:141], 2, v[74:75]
	v_lshl_add_u64 v[90:91], v[88:89], 0, s[70:71]
	v_add_co_u32_e32 v88, vcc, 0x2108000, v88
	s_nop 1
	v_addc_co_u32_e32 v89, vcc, 0, v89, vcc
	global_store_dwordx4 v[88:89], v[68:71], off
	global_store_dwordx4 v[90:91], v[64:67], off offset:16
; __device__ __forceinline__ void st_bf16x8(bf16_t* p, const f32x4 a, const f32x4 b) { uint4 o; o.x = cvt_pk_bf16(a[0], a[1]); o.y = cvt_pk_bf16(a[2], a[3]); o.z = cvt_pk_bf16(b[0], b[1]); o.w = cvt_pk_bf16(b[2], b[3]); *(uint4*)p = o; }
;     __device__ __forceinline__ void row(const f32x4 (&a)[2][2], int row, int pn, int wc, int fq) const {
;     ...
;             for (int bj = 0; bj < 2; ++bj) { const int d = head * 64 + bj * 32 + 8 * fq;
;                 const f32x4 v0 = g[bj][0] * rs * *(const f32x4*)(g_v + d), v1 = g[bj][1] * rs * *(const f32x4*)(g_v + d + 4);
;                 st_bf16x8(pV + (size_t)row * 512 + d, v0, v1);
;                 if (row >= NP && row < NTOK) { float* o = out + O_VS + (size_t)(row - NP) * 512 + d; *(f32x4*)o = v0; *(f32x4*)(o + 4) = v1; } }
.LBB0_298:
	s_or_b64 exec, exec, s[0:1]
	v_mov_b64_e32 v[64:65], v[212:213]
	v_mov_b64_e32 v[66:67], v[214:215]
	v_mov_b64_e32 v[68:69], v[216:217]
	v_mov_b64_e32 v[70:71], v[218:219]
	v_mov_b32_e32 v87, v86
	v_mov_b32_e32 v88, v86
	v_mov_b32_e32 v89, v86
	v_pk_mul_f32 v[78:79], v[78:79], v[86:87]
	v_pk_mul_f32 v[80:81], v[80:81], v[88:89]
	v_pk_mul_f32 v[82:83], v[82:83], v[86:87]
	v_pk_mul_f32 v[84:85], v[84:85], v[88:89]
	v_pk_mul_f32 v[66:67], v[80:81], v[66:67]
	v_pk_mul_f32 v[64:65], v[78:79], v[64:65]
	v_pk_mul_f32 v[70:71], v[84:85], v[70:71]
	v_pk_mul_f32 v[68:69], v[82:83], v[68:69]
	v_cvt_pk_bf16_f32 v78, v64, v65
	v_cvt_pk_bf16_f32 v79, v66, v67
	v_cvt_pk_bf16_f32 v81, v70, v71
	s_nop 0
	v_cvt_pk_bf16_f32 v80, v68, v69
	s_mov_b64 s[100:101], vcc
	v_and_b32_e32 v222, 1, v72
	s_movk_i32 s32, 0xfc40
	v_mad_i64_i32 v[76:77], s[98:99], v222, s32, v[76:77]
	v_cmp_eq_u32_e32 vcc, 0, v222
	s_nop 1
	v_cndmask_b32_dpp v200, v78, v196, vcc quad_perm:[1,0,3,2] row_mask:0xf bank_mask:0xf
	v_cndmask_b32_dpp v201, v79, v197, vcc quad_perm:[1,0,3,2] row_mask:0xf bank_mask:0xf
	v_cndmask_b32_dpp v202, v80, v198, vcc quad_perm:[1,0,3,2] row_mask:0xf bank_mask:0xf
	v_cndmask_b32_dpp v203, v81, v199, vcc quad_perm:[1,0,3,2] row_mask:0xf bank_mask:0xf
	v_cmp_ne_u32_e32 vcc, 0, v222
	s_nop 1
	v_cndmask_b32_dpp v78, v196, v78, vcc quad_perm:[1,0,3,2] row_mask:0xf bank_mask:0xf
	v_cndmask_b32_dpp v79, v197, v79, vcc quad_perm:[1,0,3,2] row_mask:0xf bank_mask:0xf
	v_cndmask_b32_dpp v80, v198, v80, vcc quad_perm:[1,0,3,2] row_mask:0xf bank_mask:0xf
	v_cndmask_b32_dpp v81, v199, v81, vcc quad_perm:[1,0,3,2] row_mask:0xf bank_mask:0xf
	global_store_dwordx4 v[76:77], v[200:203], off
	global_store_dwordx4 v[76:77], v[78:81], off offset:1024
	s_mov_b64 vcc, s[100:101]
	s_and_saveexec_b64 s[0:1], s[10:11]
	s_cbranch_execz .LBB0_300
	v_lshl_add_u64 v[74:75], v[152:153], 2, v[74:75]
	v_lshl_add_u64 v[76:77], v[74:75], 0, s[70:71]
	v_add_co_u32_e32 v74, vcc, 0x2108000, v74
	s_nop 1
	v_addc_co_u32_e32 v75, vcc, 0, v75, vcc
	global_store_dwordx4 v[74:75], v[64:67], off
	global_store_dwordx4 v[76:77], v[68:71], off offset:16

; __device__ __forceinline__ float gelu_tanh(float x) { const float u = 1.5957691216f * (x + 0.044715f * x * x * x); return x * __builtin_amdgcn_rcpf(1.f + __expf(-u)); }
; __device__ __forceinline__ void st_bf16x8(bf16_t* p, const f32x4 a, const f32x4 b) { uint4 o; o.x = cvt_pk_bf16(a[0], a[1]); o.y = cvt_pk_bf16(a[2], a[3]); o.z = cvt_pk_bf16(b[0], b[1]); o.w = cvt_pk_bf16(b[2], b[3]); *(uint4*)p = o; }
;     __device__ __forceinline__ void row(const f32x4 (&a)[2][2], int row, int pn, int wc, int fq) const {
;     ...
;             const int head = (pn - 2) * 4 + wc;
;             f32x4 g[2][2]; float ss = 0.f;
; #pragma unroll
;             for (int bj = 0; bj < 2; ++bj)
; #pragma unroll
;                 for (int n = 0; n < 2; ++n)
; #pragma unroll
;                     for (int j = 0; j < 4; ++j) { const float t = gelu_tanh(a[bj][n][j]); g[bj][n][j] = t; ss += t * t; }
;             ss += __shfl_xor(ss, 16); ss += __shfl_xor(ss, 32);
;             const float rs = rsqrtf(ss * (1.f / 64.f) + EPS);
; #pragma unroll
;             for (int bj = 0; bj < 2; ++bj) { const int d = head * 64 + bj * 32 + 8 * fq;
;                 const f32x4 v0 = g[bj][0] * rs * *(const f32x4*)(g_v + d), v1 = g[bj][1] * rs * *(const f32x4*)(g_v + d + 4);
;                 st_bf16x8(pV + (size_t)row * 512 + d, v0, v1);
.LBB0_311:
	s_andn2_b64 vcc, exec, s[0:1]
	s_cbranch_vccnz .LBB0_317
	v_mov_b32_e32 v190, 0x3d372713
	v_mov_b32_e32 v192, 0xbfcc422a
	v_mov_b32_e32 v194, 0x3fb8aa3b
	v_pk_mul_f32 v[48:49], v[44:45], v[190:191] op_sel_hi:[1,0]
	v_pk_mul_f32 v[52:53], v[46:47], v[190:191] op_sel_hi:[1,0]
	v_pk_mul_f32 v[58:59], v[40:41], v[190:191] op_sel_hi:[1,0]
	v_pk_mul_f32 v[60:61], v[42:43], v[190:191] op_sel_hi:[1,0]
	v_pk_mul_f32 v[62:63], v[36:37], v[190:191] op_sel_hi:[1,0]
	v_pk_mul_f32 v[64:65], v[38:39], v[190:191] op_sel_hi:[1,0]
	v_pk_mul_f32 v[66:67], v[32:33], v[190:191] op_sel_hi:[1,0]
	v_pk_mul_f32 v[68:69], v[34:35], v[190:191] op_sel_hi:[1,0]
	v_pk_mul_f32 v[48:49], v[44:45], v[48:49]
	v_pk_mul_f32 v[52:53], v[46:47], v[52:53]
	v_pk_mul_f32 v[58:59], v[40:41], v[58:59]
	v_pk_mul_f32 v[60:61], v[42:43], v[60:61]
	v_pk_mul_f32 v[62:63], v[36:37], v[62:63]
	v_pk_mul_f32 v[64:65], v[38:39], v[64:65]
	v_pk_mul_f32 v[66:67], v[32:33], v[66:67]
	v_pk_mul_f32 v[68:69], v[34:35], v[68:69]
	v_pk_fma_f32 v[48:49], v[44:45], v[48:49], v[44:45]
	v_pk_fma_f32 v[52:53], v[46:47], v[52:53], v[46:47]
	v_pk_fma_f32 v[58:59], v[40:41], v[58:59], v[40:41]
	v_pk_fma_f32 v[60:61], v[42:43], v[60:61], v[42:43]
	v_pk_fma_f32 v[62:63], v[36:37], v[62:63], v[36:37]
	v_pk_fma_f32 v[64:65], v[38:39], v[64:65], v[38:39]
	v_pk_fma_f32 v[66:67], v[32:33], v[66:67], v[32:33]
	v_pk_fma_f32 v[68:69], v[34:35], v[68:69], v[34:35]
	v_pk_mul_f32 v[48:49], v[48:49], v[192:193] op_sel_hi:[1,0]
	v_pk_mul_f32 v[52:53], v[52:53], v[192:193] op_sel_hi:[1,0]
	v_pk_mul_f32 v[58:59], v[58:59], v[192:193] op_sel_hi:[1,0]
	v_pk_mul_f32 v[60:61], v[60:61], v[192:193] op_sel_hi:[1,0]
	v_pk_mul_f32 v[62:63], v[62:63], v[192:193] op_sel_hi:[1,0]
	v_pk_mul_f32 v[64:65], v[64:65], v[192:193] op_sel_hi:[1,0]
	v_pk_mul_f32 v[66:67], v[66:67], v[192:193] op_sel_hi:[1,0]
	v_pk_mul_f32 v[68:69], v[68:69], v[192:193] op_sel_hi:[1,0]
	v_pk_mul_f32 v[48:49], v[48:49], v[194:195] op_sel_hi:[1,0]
	v_pk_mul_f32 v[52:53], v[52:53], v[194:195] op_sel_hi:[1,0]
	v_pk_mul_f32 v[58:59], v[58:59], v[194:195] op_sel_hi:[1,0]
	v_pk_mul_f32 v[60:61], v[60:61], v[194:195] op_sel_hi:[1,0]
	v_pk_mul_f32 v[62:63], v[62:63], v[194:195] op_sel_hi:[1,0]
	v_pk_mul_f32 v[64:65], v[64:65], v[194:195] op_sel_hi:[1,0]
	v_pk_mul_f32 v[66:67], v[66:67], v[194:195] op_sel_hi:[1,0]
	v_pk_mul_f32 v[68:69], v[68:69], v[194:195] op_sel_hi:[1,0]
	v_exp_f32_e32 v48, v48
	v_exp_f32_e32 v49, v49
	v_exp_f32_e32 v52, v52
	v_exp_f32_e32 v53, v53
	v_exp_f32_e32 v58, v58
	v_exp_f32_e32 v59, v59
	v_exp_f32_e32 v60, v60
	v_exp_f32_e32 v61, v61
	v_exp_f32_e32 v62, v62
	v_exp_f32_e32 v63, v63
	v_exp_f32_e32 v64, v64
	v_exp_f32_e32 v65, v65
	v_exp_f32_e32 v66, v66
	v_exp_f32_e32 v67, v67
	v_exp_f32_e32 v68, v68
	v_exp_f32_e32 v69, v69
	v_pk_add_f32 v[48:49], v[48:49], 1.0 op_sel_hi:[1,0]
	v_pk_add_f32 v[52:53], v[52:53], 1.0 op_sel_hi:[1,0]
	v_pk_add_f32 v[58:59], v[58:59], 1.0 op_sel_hi:[1,0]
	v_pk_add_f32 v[60:61], v[60:61], 1.0 op_sel_hi:[1,0]
	v_pk_add_f32 v[62:63], v[62:63], 1.0 op_sel_hi:[1,0]
	v_pk_add_f32 v[64:65], v[64:65], 1.0 op_sel_hi:[1,0]
	v_pk_add_f32 v[66:67], v[66:67], 1.0 op_sel_hi:[1,0]
	v_pk_add_f32 v[68:69], v[68:69], 1.0 op_sel_hi:[1,0]
	v_rcp_f32_e32 v48, v48
	v_rcp_f32_e32 v49, v49
	v_rcp_f32_e32 v52, v52
	v_rcp_f32_e32 v53, v53
	v_rcp_f32_e32 v58, v58
	v_rcp_f32_e32 v59, v59
	v_rcp_f32_e32 v60, v60
	v_rcp_f32_e32 v61, v61
	v_rcp_f32_e32 v62, v62
	v_rcp_f32_e32 v63, v63
	v_rcp_f32_e32 v64, v64
	v_rcp_f32_e32 v65, v65
	v_rcp_f32_e32 v66, v66
	v_rcp_f32_e32 v67, v67
	v_rcp_f32_e32 v68, v68
	v_rcp_f32_e32 v69, v69
	v_pk_mul_f32 v[48:49], v[44:45], v[48:49]
	v_pk_mul_f32 v[52:53], v[46:47], v[52:53]
	v_pk_mul_f32 v[58:59], v[40:41], v[58:59]
	v_pk_mul_f32 v[60:61], v[42:43], v[60:61]
	v_pk_mul_f32 v[62:63], v[36:37], v[62:63]
	v_pk_mul_f32 v[64:65], v[38:39], v[64:65]
	v_pk_mul_f32 v[66:67], v[32:33], v[66:67]
	v_pk_mul_f32 v[68:69], v[34:35], v[68:69]
	v_pk_mul_f32 v[50:51], v[48:49], v[48:49]
	v_pk_mul_f32 v[54:55], v[52:53], v[52:53]
	v_add_f32_e32 v50, v50, v51
	v_add_f32_e32 v50, v54, v50
	v_pk_mul_f32 v[70:71], v[58:59], v[58:59]
	v_add_f32_e32 v50, v55, v50
	v_add_f32_e32 v50, v70, v50
	v_pk_mul_f32 v[74:75], v[60:61], v[60:61]
	v_add_f32_e32 v50, v71, v50
	v_add_f32_e32 v50, v74, v50
	v_pk_mul_f32 v[76:77], v[62:63], v[62:63]
	v_add_f32_e32 v50, v75, v50
	v_add_f32_e32 v50, v50, v76
	v_pk_mul_f32 v[78:79], v[64:65], v[64:65]
	v_add_f32_e32 v50, v77, v50
	v_add_f32_e32 v50, v78, v50
	v_pk_mul_f32 v[80:81], v[66:67], v[66:67]
	v_add_f32_e32 v50, v79, v50
	v_add_f32_e32 v50, v80, v50
	v_pk_mul_f32 v[82:83], v[68:69], v[68:69]
	v_add_f32_e32 v50, v81, v50
	v_add_f32_e32 v50, v82, v50
	v_add_f32_e32 v50, v83, v50
	ds_bpermute_b32 v51, v229, v50
	v_lshl_add_u64 v[82:83], v[140:141], 2, s[18:19]
	v_ashrrev_i32_e32 v57, 31, v56
	v_lshlrev_b64 v[76:77], 10, v[56:57]
	v_lshlrev_b32_e32 v74, 9, v56
	s_waitcnt lgkmcnt(0)
	v_add_f32_e32 v50, v50, v51
	ds_bpermute_b32 v51, v230, v50
	v_mov_b32_e32 v75, v141
	s_waitcnt lgkmcnt(0)
	v_add_f32_e32 v50, v50, v51
	v_fmamk_f32 v50, v50, 0x3c800000, v188
	v_cmp_gt_f32_e32 vcc, s13, v50
	v_mul_f32_e32 v51, 0x4b800000, v50
	s_nop 0
	v_cndmask_b32_e32 v50, v50, v51, vcc
	v_rsq_f32_e32 v50, v50
	s_nop 0
	v_mul_f32_e32 v51, 0x45800000, v50
	v_cndmask_b32_e32 v70, v50, v51, vcc
	v_pk_mul_f32 v[78:79], v[48:49], v[70:71] op_sel_hi:[1,0]
	v_pk_mul_f32 v[80:81], v[52:53], v[70:71] op_sel_hi:[1,0]
	v_mov_b64_e32 v[48:49], v[208:209]
	v_mov_b64_e32 v[50:51], v[210:211]
	v_mov_b64_e32 v[52:53], v[204:205]
	v_mov_b64_e32 v[54:55], v[206:207]
	v_pk_mul_f32 v[58:59], v[58:59], v[70:71] op_sel_hi:[1,0]
	v_pk_mul_f32 v[60:61], v[60:61], v[70:71] op_sel_hi:[1,0]
	v_pk_mul_f32 v[48:49], v[48:49], v[58:59]
	v_lshl_add_u64 v[58:59], s[46:47], 0, v[76:77]
	v_pk_mul_f32 v[54:55], v[54:55], v[80:81]
	v_pk_mul_f32 v[52:53], v[52:53], v[78:79]
	v_pk_mul_f32 v[50:51], v[50:51], v[60:61]
	v_lshl_add_u64 v[60:61], v[140:141], 1, v[58:59]
	v_lshl_add_u64 v[58:59], v[74:75], 2, s[56:57]
	v_cvt_pk_bf16_f32 v76, v52, v53
	v_cvt_pk_bf16_f32 v77, v54, v55
	v_cvt_pk_bf16_f32 v78, v48, v49
	v_cvt_pk_bf16_f32 v79, v50, v51
	v_mov_b64_e32 v[196:197], v[76:77]
	v_mov_b64_e32 v[198:199], v[78:79]
	s_and_saveexec_b64 s[0:1], s[10:11]
	s_cbranch_execz .LBB0_314
	v_lshl_add_u64 v[74:75], v[140:141], 2, v[58:59]
	v_lshl_add_u64 v[76:77], v[74:75], 0, s[70:71]
	v_add_co_u32_e32 v74, vcc, 0x2108000, v74
	s_nop 1
	v_addc_co_u32_e32 v75, vcc, 0, v75, vcc
	global_store_dwordx4 v[74:75], v[52:55], off
	global_store_dwordx4 v[76:77], v[48:51], off offset:16
; __device__ __forceinline__ void st_bf16x8(bf16_t* p, const f32x4 a, const f32x4 b) { uint4 o; o.x = cvt_pk_bf16(a[0], a[1]); o.y = cvt_pk_bf16(a[2], a[3]); o.z = cvt_pk_bf16(b[0], b[1]); o.w = cvt_pk_bf16(b[2], b[3]); *(uint4*)p = o; }
;     __device__ __forceinline__ void row(const f32x4 (&a)[2][2], int row, int pn, int wc, int fq) const {
;     ...
;             for (int bj = 0; bj < 2; ++bj) { const int d = head * 64 + bj * 32 + 8 * fq;
;                 const f32x4 v0 = g[bj][0] * rs * *(const f32x4*)(g_v + d), v1 = g[bj][1] * rs * *(const f32x4*)(g_v + d + 4);
;                 st_bf16x8(pV + (size_t)row * 512 + d, v0, v1);
;                 if (row >= NP && row < NTOK) { float* o = out + O_VS + (size_t)(row - NP) * 512 + d; *(f32x4*)o = v0; *(f32x4*)(o + 4) = v1; } }
.LBB0_314:
	s_or_b64 exec, exec, s[0:1]
	v_mov_b64_e32 v[48:49], v[212:213]
	v_mov_b64_e32 v[50:51], v[214:215]
	v_mov_b64_e32 v[52:53], v[216:217]
	v_mov_b64_e32 v[54:55], v[218:219]
	v_mov_b32_e32 v71, v70
	v_mov_b32_e32 v74, v70
	v_mov_b32_e32 v75, v70
	v_pk_mul_f32 v[62:63], v[62:63], v[70:71]
	v_pk_mul_f32 v[64:65], v[64:65], v[74:75]
	v_pk_mul_f32 v[66:67], v[66:67], v[70:71]
	v_pk_mul_f32 v[68:69], v[68:69], v[74:75]
	v_pk_mul_f32 v[50:51], v[64:65], v[50:51]
	v_pk_mul_f32 v[48:49], v[62:63], v[48:49]
	v_pk_mul_f32 v[54:55], v[68:69], v[54:55]
	v_pk_mul_f32 v[52:53], v[66:67], v[52:53]
	v_cvt_pk_bf16_f32 v62, v48, v49
	v_cvt_pk_bf16_f32 v63, v50, v51
	v_cvt_pk_bf16_f32 v65, v54, v55
	s_nop 0
	v_cvt_pk_bf16_f32 v64, v52, v53
	s_mov_b64 s[100:101], vcc
	v_and_b32_e32 v222, 1, v56
	s_movk_i32 s32, 0xfc40
	v_mad_i64_i32 v[60:61], s[98:99], v222, s32, v[60:61]
	v_cmp_eq_u32_e32 vcc, 0, v222
	s_nop 1
	v_cndmask_b32_dpp v200, v62, v196, vcc quad_perm:[1,0,3,2] row_mask:0xf bank_mask:0xf
	v_cndmask_b32_dpp v201, v63, v197, vcc quad_perm:[1,0,3,2] row_mask:0xf bank_mask:0xf
	v_cndmask_b32_dpp v202, v64, v198, vcc quad_perm:[1,0,3,2] row_mask:0xf bank_mask:0xf
	v_cndmask_b32_dpp v203, v65, v199, vcc quad_perm:[1,0,3,2] row_mask:0xf bank_mask:0xf
	v_cmp_ne_u32_e32 vcc, 0, v222
	s_nop 1
	v_cndmask_b32_dpp v62, v196, v62, vcc quad_perm:[1,0,3,2] row_mask:0xf bank_mask:0xf
	v_cndmask_b32_dpp v63, v197, v63, vcc quad_perm:[1,0,3,2] row_mask:0xf bank_mask:0xf
	v_cndmask_b32_dpp v64, v198, v64, vcc quad_perm:[1,0,3,2] row_mask:0xf bank_mask:0xf
	v_cndmask_b32_dpp v65, v199, v65, vcc quad_perm:[1,0,3,2] row_mask:0xf bank_mask:0xf
	global_store_dwordx4 v[60:61], v[200:203], off
	global_store_dwordx4 v[60:61], v[62:65], off offset:1024
	s_mov_b64 vcc, s[100:101]
	s_and_saveexec_b64 s[0:1], s[10:11]
	s_cbranch_execz .LBB0_316
	v_lshl_add_u64 v[58:59], v[152:153], 2, v[58:59]
	v_lshl_add_u64 v[60:61], v[58:59], 0, s[70:71]
	v_add_co_u32_e32 v58, vcc, 0x2108000, v58
	s_nop 1
	v_addc_co_u32_e32 v59, vcc, 0, v59, vcc
	global_store_dwordx4 v[58:59], v[48:51], off
	global_store_dwordx4 v[60:61], v[52:55], off offset:16

; __device__ __forceinline__ float gelu_tanh(float x) { const float u = 1.5957691216f * (x + 0.044715f * x * x * x); return x * __builtin_amdgcn_rcpf(1.f + __expf(-u)); }
; __device__ __forceinline__ void st_bf16x8(bf16_t* p, const f32x4 a, const f32x4 b) { uint4 o; o.x = cvt_pk_bf16(a[0], a[1]); o.y = cvt_pk_bf16(a[2], a[3]); o.z = cvt_pk_bf16(b[0], b[1]); o.w = cvt_pk_bf16(b[2], b[3]); *(uint4*)p = o; }
;     __device__ __forceinline__ void row(const f32x4 (&a)[2][2], int row, int pn, int wc, int fq) const {
;     ...
;             const int head = (pn - 2) * 4 + wc;
;             f32x4 g[2][2]; float ss = 0.f;
; #pragma unroll
;             for (int bj = 0; bj < 2; ++bj)
; #pragma unroll
;                 for (int n = 0; n < 2; ++n)
; #pragma unroll
;                     for (int j = 0; j < 4; ++j) { const float t = gelu_tanh(a[bj][n][j]); g[bj][n][j] = t; ss += t * t; }
;             ss += __shfl_xor(ss, 16); ss += __shfl_xor(ss, 32);
;             const float rs = rsqrtf(ss * (1.f / 64.f) + EPS);
; #pragma unroll
;             for (int bj = 0; bj < 2; ++bj) { const int d = head * 64 + bj * 32 + 8 * fq;
;                 const f32x4 v0 = g[bj][0] * rs * *(const f32x4*)(g_v + d), v1 = g[bj][1] * rs * *(const f32x4*)(g_v + d + 4);
;                 st_bf16x8(pV + (size_t)row * 512 + d, v0, v1);
.LBB0_327:
	s_andn2_b64 vcc, exec, s[0:1]
	s_cbranch_vccnz .LBB0_333
	v_mov_b32_e32 v190, 0x3d372713
	v_mov_b32_e32 v192, 0xbfcc422a
	v_mov_b32_e32 v194, 0x3fb8aa3b
	v_pk_mul_f32 v[32:33], v[28:29], v[190:191] op_sel_hi:[1,0]
	v_pk_mul_f32 v[36:37], v[30:31], v[190:191] op_sel_hi:[1,0]
	v_pk_mul_f32 v[42:43], v[24:25], v[190:191] op_sel_hi:[1,0]
	v_pk_mul_f32 v[44:45], v[26:27], v[190:191] op_sel_hi:[1,0]
	v_pk_mul_f32 v[46:47], v[20:21], v[190:191] op_sel_hi:[1,0]
	v_pk_mul_f32 v[48:49], v[22:23], v[190:191] op_sel_hi:[1,0]
	v_pk_mul_f32 v[50:51], v[16:17], v[190:191] op_sel_hi:[1,0]
	v_pk_mul_f32 v[52:53], v[18:19], v[190:191] op_sel_hi:[1,0]
	v_pk_mul_f32 v[32:33], v[28:29], v[32:33]
	v_pk_mul_f32 v[36:37], v[30:31], v[36:37]
	v_pk_mul_f32 v[42:43], v[24:25], v[42:43]
	v_pk_mul_f32 v[44:45], v[26:27], v[44:45]
	v_pk_mul_f32 v[46:47], v[20:21], v[46:47]
	v_pk_mul_f32 v[48:49], v[22:23], v[48:49]
	v_pk_mul_f32 v[50:51], v[16:17], v[50:51]
	v_pk_mul_f32 v[52:53], v[18:19], v[52:53]
	v_pk_fma_f32 v[32:33], v[28:29], v[32:33], v[28:29]
	v_pk_fma_f32 v[36:37], v[30:31], v[36:37], v[30:31]
	v_pk_fma_f32 v[42:43], v[24:25], v[42:43], v[24:25]
	v_pk_fma_f32 v[44:45], v[26:27], v[44:45], v[26:27]
	v_pk_fma_f32 v[46:47], v[20:21], v[46:47], v[20:21]
	v_pk_fma_f32 v[48:49], v[22:23], v[48:49], v[22:23]
	v_pk_fma_f32 v[50:51], v[16:17], v[50:51], v[16:17]
	v_pk_fma_f32 v[52:53], v[18:19], v[52:53], v[18:19]
	v_pk_mul_f32 v[32:33], v[32:33], v[192:193] op_sel_hi:[1,0]
	v_pk_mul_f32 v[36:37], v[36:37], v[192:193] op_sel_hi:[1,0]
	v_pk_mul_f32 v[42:43], v[42:43], v[192:193] op_sel_hi:[1,0]
	v_pk_mul_f32 v[44:45], v[44:45], v[192:193] op_sel_hi:[1,0]
	v_pk_mul_f32 v[46:47], v[46:47], v[192:193] op_sel_hi:[1,0]
	v_pk_mul_f32 v[48:49], v[48:49], v[192:193] op_sel_hi:[1,0]
	v_pk_mul_f32 v[50:51], v[50:51], v[192:193] op_sel_hi:[1,0]
	v_pk_mul_f32 v[52:53], v[52:53], v[192:193] op_sel_hi:[1,0]
	v_pk_mul_f32 v[32:33], v[32:33], v[194:195] op_sel_hi:[1,0]
	v_pk_mul_f32 v[36:37], v[36:37], v[194:195] op_sel_hi:[1,0]
	v_pk_mul_f32 v[42:43], v[42:43], v[194:195] op_sel_hi:[1,0]
	v_pk_mul_f32 v[44:45], v[44:45], v[194:195] op_sel_hi:[1,0]
	v_pk_mul_f32 v[46:47], v[46:47], v[194:195] op_sel_hi:[1,0]
	v_pk_mul_f32 v[48:49], v[48:49], v[194:195] op_sel_hi:[1,0]
	v_pk_mul_f32 v[50:51], v[50:51], v[194:195] op_sel_hi:[1,0]
	v_pk_mul_f32 v[52:53], v[52:53], v[194:195] op_sel_hi:[1,0]
	v_exp_f32_e32 v32, v32
	v_exp_f32_e32 v33, v33
	v_exp_f32_e32 v36, v36
	v_exp_f32_e32 v37, v37
	v_exp_f32_e32 v42, v42
	v_exp_f32_e32 v43, v43
	v_exp_f32_e32 v44, v44
	v_exp_f32_e32 v45, v45
	v_exp_f32_e32 v46, v46
	v_exp_f32_e32 v47, v47
	v_exp_f32_e32 v48, v48
	v_exp_f32_e32 v49, v49
	v_exp_f32_e32 v50, v50
	v_exp_f32_e32 v51, v51
	v_exp_f32_e32 v52, v52
	v_exp_f32_e32 v53, v53
	v_pk_add_f32 v[32:33], v[32:33], 1.0 op_sel_hi:[1,0]
	v_pk_add_f32 v[36:37], v[36:37], 1.0 op_sel_hi:[1,0]
	v_pk_add_f32 v[42:43], v[42:43], 1.0 op_sel_hi:[1,0]
	v_pk_add_f32 v[44:45], v[44:45], 1.0 op_sel_hi:[1,0]
	v_pk_add_f32 v[46:47], v[46:47], 1.0 op_sel_hi:[1,0]
	v_pk_add_f32 v[48:49], v[48:49], 1.0 op_sel_hi:[1,0]
	v_pk_add_f32 v[50:51], v[50:51], 1.0 op_sel_hi:[1,0]
	v_pk_add_f32 v[52:53], v[52:53], 1.0 op_sel_hi:[1,0]
	v_rcp_f32_e32 v32, v32
	v_rcp_f32_e32 v33, v33
	v_rcp_f32_e32 v36, v36
	v_rcp_f32_e32 v37, v37
	v_rcp_f32_e32 v42, v42
	v_rcp_f32_e32 v43, v43
	v_rcp_f32_e32 v44, v44
	v_rcp_f32_e32 v45, v45
	v_rcp_f32_e32 v46, v46
	v_rcp_f32_e32 v47, v47
	v_rcp_f32_e32 v48, v48
	v_rcp_f32_e32 v49, v49
	v_rcp_f32_e32 v50, v50
	v_rcp_f32_e32 v51, v51
	v_rcp_f32_e32 v52, v52
	v_rcp_f32_e32 v53, v53
	v_pk_mul_f32 v[32:33], v[28:29], v[32:33]
	v_pk_mul_f32 v[36:37], v[30:31], v[36:37]
	v_pk_mul_f32 v[42:43], v[24:25], v[42:43]
	v_pk_mul_f32 v[44:45], v[26:27], v[44:45]
	v_pk_mul_f32 v[46:47], v[20:21], v[46:47]
	v_pk_mul_f32 v[48:49], v[22:23], v[48:49]
	v_pk_mul_f32 v[50:51], v[16:17], v[50:51]
	v_pk_mul_f32 v[52:53], v[18:19], v[52:53]
	v_pk_mul_f32 v[34:35], v[32:33], v[32:33]
	v_pk_mul_f32 v[38:39], v[36:37], v[36:37]
	v_add_f32_e32 v34, v34, v35
	v_add_f32_e32 v34, v38, v34
	v_pk_mul_f32 v[54:55], v[42:43], v[42:43]
	v_add_f32_e32 v34, v39, v34
	v_add_f32_e32 v34, v54, v34
	v_pk_mul_f32 v[56:57], v[44:45], v[44:45]
	v_add_f32_e32 v34, v55, v34
	v_add_f32_e32 v34, v56, v34
	v_pk_mul_f32 v[58:59], v[46:47], v[46:47]
	v_add_f32_e32 v34, v57, v34
	v_add_f32_e32 v34, v34, v58
	v_pk_mul_f32 v[60:61], v[48:49], v[48:49]
	v_add_f32_e32 v34, v59, v34
	v_add_f32_e32 v34, v60, v34
	v_pk_mul_f32 v[62:63], v[50:51], v[50:51]
	v_add_f32_e32 v34, v61, v34
	v_add_f32_e32 v34, v62, v34
	v_pk_mul_f32 v[64:65], v[52:53], v[52:53]
	v_add_f32_e32 v34, v63, v34
	v_add_f32_e32 v34, v64, v34
	v_add_f32_e32 v34, v65, v34
	ds_bpermute_b32 v35, v229, v34
	v_lshl_add_u64 v[64:65], v[140:141], 2, s[18:19]
	v_ashrrev_i32_e32 v41, 31, v40
	v_lshlrev_b64 v[58:59], 10, v[40:41]
	v_lshlrev_b32_e32 v56, 9, v40
	s_waitcnt lgkmcnt(0)
	v_add_f32_e32 v34, v34, v35
	ds_bpermute_b32 v35, v230, v34
	v_mov_b32_e32 v57, v141
	s_waitcnt lgkmcnt(0)
	v_add_f32_e32 v34, v34, v35
	v_fmamk_f32 v34, v34, 0x3c800000, v188
	v_cmp_gt_f32_e32 vcc, s13, v34
	v_mul_f32_e32 v35, 0x4b800000, v34
	s_nop 0
	v_cndmask_b32_e32 v34, v34, v35, vcc
	v_rsq_f32_e32 v34, v34
	s_nop 0
	v_mul_f32_e32 v35, 0x45800000, v34
	v_cndmask_b32_e32 v54, v34, v35, vcc
	v_pk_mul_f32 v[60:61], v[32:33], v[54:55] op_sel_hi:[1,0]
	v_pk_mul_f32 v[62:63], v[36:37], v[54:55] op_sel_hi:[1,0]
	v_mov_b64_e32 v[32:33], v[208:209]
	v_mov_b64_e32 v[34:35], v[210:211]
	v_mov_b64_e32 v[36:37], v[204:205]
	v_mov_b64_e32 v[38:39], v[206:207]
	v_pk_mul_f32 v[42:43], v[42:43], v[54:55] op_sel_hi:[1,0]
	v_pk_mul_f32 v[44:45], v[44:45], v[54:55] op_sel_hi:[1,0]
	v_pk_mul_f32 v[32:33], v[32:33], v[42:43]
	v_lshl_add_u64 v[42:43], s[46:47], 0, v[58:59]
	v_pk_mul_f32 v[38:39], v[38:39], v[62:63]
	v_pk_mul_f32 v[36:37], v[36:37], v[60:61]
	v_pk_mul_f32 v[34:35], v[34:35], v[44:45]
	v_lshl_add_u64 v[44:45], v[140:141], 1, v[42:43]
	v_lshl_add_u64 v[42:43], v[56:57], 2, s[56:57]
	v_cvt_pk_bf16_f32 v58, v36, v37
	v_cvt_pk_bf16_f32 v59, v38, v39
	v_cvt_pk_bf16_f32 v60, v32, v33
	v_cvt_pk_bf16_f32 v61, v34, v35
	v_mov_b64_e32 v[196:197], v[58:59]
	v_mov_b64_e32 v[198:199], v[60:61]
	s_and_saveexec_b64 s[0:1], s[10:11]
	s_cbranch_execz .LBB0_330
	v_lshl_add_u64 v[56:57], v[140:141], 2, v[42:43]
	v_lshl_add_u64 v[58:59], v[56:57], 0, s[70:71]
	v_add_co_u32_e32 v56, vcc, 0x2108000, v56
	s_nop 1
	v_addc_co_u32_e32 v57, vcc, 0, v57, vcc
	global_store_dwordx4 v[56:57], v[36:39], off
	global_store_dwordx4 v[58:59], v[32:35], off offset:16
; __device__ __forceinline__ void st_bf16x8(bf16_t* p, const f32x4 a, const f32x4 b) { uint4 o; o.x = cvt_pk_bf16(a[0], a[1]); o.y = cvt_pk_bf16(a[2], a[3]); o.z = cvt_pk_bf16(b[0], b[1]); o.w = cvt_pk_bf16(b[2], b[3]); *(uint4*)p = o; }
;     __device__ __forceinline__ void row(const f32x4 (&a)[2][2], int row, int pn, int wc, int fq) const {
;     ...
;             for (int bj = 0; bj < 2; ++bj) { const int d = head * 64 + bj * 32 + 8 * fq;
;                 const f32x4 v0 = g[bj][0] * rs * *(const f32x4*)(g_v + d), v1 = g[bj][1] * rs * *(const f32x4*)(g_v + d + 4);
;                 st_bf16x8(pV + (size_t)row * 512 + d, v0, v1);
;                 if (row >= NP && row < NTOK) { float* o = out + O_VS + (size_t)(row - NP) * 512 + d; *(f32x4*)o = v0; *(f32x4*)(o + 4) = v1; } }
.LBB0_330:
	s_or_b64 exec, exec, s[0:1]
	v_mov_b64_e32 v[32:33], v[212:213]
	v_mov_b64_e32 v[34:35], v[214:215]
	v_mov_b64_e32 v[36:37], v[216:217]
	v_mov_b64_e32 v[38:39], v[218:219]
	v_mov_b32_e32 v55, v54
	v_mov_b32_e32 v56, v54
	v_mov_b32_e32 v57, v54
	v_pk_mul_f32 v[46:47], v[46:47], v[54:55]
	v_pk_mul_f32 v[48:49], v[48:49], v[56:57]
	v_pk_mul_f32 v[50:51], v[50:51], v[54:55]
	v_pk_mul_f32 v[52:53], v[52:53], v[56:57]
	v_pk_mul_f32 v[34:35], v[48:49], v[34:35]
	v_pk_mul_f32 v[32:33], v[46:47], v[32:33]
	v_pk_mul_f32 v[38:39], v[52:53], v[38:39]
	v_pk_mul_f32 v[36:37], v[50:51], v[36:37]
	v_cvt_pk_bf16_f32 v46, v32, v33
	v_cvt_pk_bf16_f32 v47, v34, v35
	v_cvt_pk_bf16_f32 v49, v38, v39
	s_nop 0
	v_cvt_pk_bf16_f32 v48, v36, v37
	s_mov_b64 s[100:101], vcc
	v_and_b32_e32 v222, 1, v40
	s_movk_i32 s32, 0xfc40
	v_mad_i64_i32 v[44:45], s[98:99], v222, s32, v[44:45]
	v_cmp_eq_u32_e32 vcc, 0, v222
	s_nop 1
	v_cndmask_b32_dpp v200, v46, v196, vcc quad_perm:[1,0,3,2] row_mask:0xf bank_mask:0xf
	v_cndmask_b32_dpp v201, v47, v197, vcc quad_perm:[1,0,3,2] row_mask:0xf bank_mask:0xf
	v_cndmask_b32_dpp v202, v48, v198, vcc quad_perm:[1,0,3,2] row_mask:0xf bank_mask:0xf
	v_cndmask_b32_dpp v203, v49, v199, vcc quad_perm:[1,0,3,2] row_mask:0xf bank_mask:0xf
	v_cmp_ne_u32_e32 vcc, 0, v222
	s_nop 1
	v_cndmask_b32_dpp v46, v196, v46, vcc quad_perm:[1,0,3,2] row_mask:0xf bank_mask:0xf
	v_cndmask_b32_dpp v47, v197, v47, vcc quad_perm:[1,0,3,2] row_mask:0xf bank_mask:0xf
	v_cndmask_b32_dpp v48, v198, v48, vcc quad_perm:[1,0,3,2] row_mask:0xf bank_mask:0xf
	v_cndmask_b32_dpp v49, v199, v49, vcc quad_perm:[1,0,3,2] row_mask:0xf bank_mask:0xf
	global_store_dwordx4 v[44:45], v[200:203], off
	global_store_dwordx4 v[44:45], v[46:49], off offset:1024
	s_mov_b64 vcc, s[100:101]
	s_and_saveexec_b64 s[0:1], s[10:11]
	s_cbranch_execz .LBB0_332
	v_lshl_add_u64 v[42:43], v[152:153], 2, v[42:43]
	v_lshl_add_u64 v[44:45], v[42:43], 0, s[70:71]
	v_add_co_u32_e32 v42, vcc, 0x2108000, v42
	s_nop 1
	v_addc_co_u32_e32 v43, vcc, 0, v43, vcc
	global_store_dwordx4 v[42:43], v[32:35], off
	global_store_dwordx4 v[44:45], v[36:39], off offset:16

; __device__ __forceinline__ float gelu_tanh(float x) { const float u = 1.5957691216f * (x + 0.044715f * x * x * x); return x * __builtin_amdgcn_rcpf(1.f + __expf(-u)); }
; __device__ __forceinline__ void st_bf16x8(bf16_t* p, const f32x4 a, const f32x4 b) { uint4 o; o.x = cvt_pk_bf16(a[0], a[1]); o.y = cvt_pk_bf16(a[2], a[3]); o.z = cvt_pk_bf16(b[0], b[1]); o.w = cvt_pk_bf16(b[2], b[3]); *(uint4*)p = o; }
;     __device__ __forceinline__ void row(const f32x4 (&a)[2][2], int row, int pn, int wc, int fq) const {
;     ...
;             const int head = (pn - 2) * 4 + wc;
;             f32x4 g[2][2]; float ss = 0.f;
; #pragma unroll
;             for (int bj = 0; bj < 2; ++bj)
; #pragma unroll
;                 for (int n = 0; n < 2; ++n)
; #pragma unroll
;                     for (int j = 0; j < 4; ++j) { const float t = gelu_tanh(a[bj][n][j]); g[bj][n][j] = t; ss += t * t; }
;             ss += __shfl_xor(ss, 16); ss += __shfl_xor(ss, 32);
;             const float rs = rsqrtf(ss * (1.f / 64.f) + EPS);
; #pragma unroll
;             for (int bj = 0; bj < 2; ++bj) { const int d = head * 64 + bj * 32 + 8 * fq;
;                 const f32x4 v0 = g[bj][0] * rs * *(const f32x4*)(g_v + d), v1 = g[bj][1] * rs * *(const f32x4*)(g_v + d + 4);
;                 st_bf16x8(pV + (size_t)row * 512 + d, v0, v1);
.LBB0_345:
	s_and_b64 vcc, exec, s[0:1]
	s_cbranch_vccz .LBB0_351
	v_mov_b32_e32 v190, 0x3d372713
	v_mov_b32_e32 v192, 0xbfcc422a
	v_mov_b32_e32 v194, 0x3fb8aa3b
	v_pk_mul_f32 v[16:17], v[12:13], v[190:191] op_sel_hi:[1,0]
	v_pk_mul_f32 v[20:21], v[14:15], v[190:191] op_sel_hi:[1,0]
	v_pk_mul_f32 v[26:27], v[8:9], v[190:191] op_sel_hi:[1,0]
	v_pk_mul_f32 v[28:29], v[10:11], v[190:191] op_sel_hi:[1,0]
	v_pk_mul_f32 v[30:31], v[4:5], v[190:191] op_sel_hi:[1,0]
	v_pk_mul_f32 v[32:33], v[6:7], v[190:191] op_sel_hi:[1,0]
	v_pk_mul_f32 v[34:35], v[0:1], v[190:191] op_sel_hi:[1,0]
	v_pk_mul_f32 v[36:37], v[2:3], v[190:191] op_sel_hi:[1,0]
	v_pk_mul_f32 v[16:17], v[12:13], v[16:17]
	v_pk_mul_f32 v[20:21], v[14:15], v[20:21]
	v_pk_mul_f32 v[26:27], v[8:9], v[26:27]
	v_pk_mul_f32 v[28:29], v[10:11], v[28:29]
	v_pk_mul_f32 v[30:31], v[4:5], v[30:31]
	v_pk_mul_f32 v[32:33], v[6:7], v[32:33]
	v_pk_mul_f32 v[34:35], v[0:1], v[34:35]
	v_pk_mul_f32 v[36:37], v[2:3], v[36:37]
	v_pk_fma_f32 v[16:17], v[12:13], v[16:17], v[12:13]
	v_pk_fma_f32 v[20:21], v[14:15], v[20:21], v[14:15]
	v_pk_fma_f32 v[26:27], v[8:9], v[26:27], v[8:9]
	v_pk_fma_f32 v[28:29], v[10:11], v[28:29], v[10:11]
	v_pk_fma_f32 v[30:31], v[4:5], v[30:31], v[4:5]
	v_pk_fma_f32 v[32:33], v[6:7], v[32:33], v[6:7]
	v_pk_fma_f32 v[34:35], v[0:1], v[34:35], v[0:1]
	v_pk_fma_f32 v[36:37], v[2:3], v[36:37], v[2:3]
	v_pk_mul_f32 v[16:17], v[16:17], v[192:193] op_sel_hi:[1,0]
	v_pk_mul_f32 v[20:21], v[20:21], v[192:193] op_sel_hi:[1,0]
	v_pk_mul_f32 v[26:27], v[26:27], v[192:193] op_sel_hi:[1,0]
	v_pk_mul_f32 v[28:29], v[28:29], v[192:193] op_sel_hi:[1,0]
	v_pk_mul_f32 v[30:31], v[30:31], v[192:193] op_sel_hi:[1,0]
	v_pk_mul_f32 v[32:33], v[32:33], v[192:193] op_sel_hi:[1,0]
	v_pk_mul_f32 v[34:35], v[34:35], v[192:193] op_sel_hi:[1,0]
	v_pk_mul_f32 v[36:37], v[36:37], v[192:193] op_sel_hi:[1,0]
	v_pk_mul_f32 v[16:17], v[16:17], v[194:195] op_sel_hi:[1,0]
	v_pk_mul_f32 v[20:21], v[20:21], v[194:195] op_sel_hi:[1,0]
	v_pk_mul_f32 v[26:27], v[26:27], v[194:195] op_sel_hi:[1,0]
	v_pk_mul_f32 v[28:29], v[28:29], v[194:195] op_sel_hi:[1,0]
	v_pk_mul_f32 v[30:31], v[30:31], v[194:195] op_sel_hi:[1,0]
	v_pk_mul_f32 v[32:33], v[32:33], v[194:195] op_sel_hi:[1,0]
	v_pk_mul_f32 v[34:35], v[34:35], v[194:195] op_sel_hi:[1,0]
	v_pk_mul_f32 v[36:37], v[36:37], v[194:195] op_sel_hi:[1,0]
	v_exp_f32_e32 v16, v16
	v_exp_f32_e32 v17, v17
	v_exp_f32_e32 v20, v20
	v_exp_f32_e32 v21, v21
	v_exp_f32_e32 v26, v26
	v_exp_f32_e32 v27, v27
	v_exp_f32_e32 v28, v28
	v_exp_f32_e32 v29, v29
	v_exp_f32_e32 v30, v30
	v_exp_f32_e32 v31, v31
	v_exp_f32_e32 v32, v32
	v_exp_f32_e32 v33, v33
	v_exp_f32_e32 v34, v34
	v_exp_f32_e32 v35, v35
	v_exp_f32_e32 v36, v36
	v_exp_f32_e32 v37, v37
	v_pk_add_f32 v[16:17], v[16:17], 1.0 op_sel_hi:[1,0]
	v_pk_add_f32 v[20:21], v[20:21], 1.0 op_sel_hi:[1,0]
	v_pk_add_f32 v[26:27], v[26:27], 1.0 op_sel_hi:[1,0]
	v_pk_add_f32 v[28:29], v[28:29], 1.0 op_sel_hi:[1,0]
	v_pk_add_f32 v[30:31], v[30:31], 1.0 op_sel_hi:[1,0]
	v_pk_add_f32 v[32:33], v[32:33], 1.0 op_sel_hi:[1,0]
	v_pk_add_f32 v[34:35], v[34:35], 1.0 op_sel_hi:[1,0]
	v_pk_add_f32 v[36:37], v[36:37], 1.0 op_sel_hi:[1,0]
	v_rcp_f32_e32 v16, v16
	v_rcp_f32_e32 v17, v17
	v_rcp_f32_e32 v20, v20
	v_rcp_f32_e32 v21, v21
	v_rcp_f32_e32 v26, v26
	v_rcp_f32_e32 v27, v27
	v_rcp_f32_e32 v28, v28
	v_rcp_f32_e32 v29, v29
	v_rcp_f32_e32 v30, v30
	v_rcp_f32_e32 v31, v31
	v_rcp_f32_e32 v32, v32
	v_rcp_f32_e32 v33, v33
	v_rcp_f32_e32 v34, v34
	v_rcp_f32_e32 v35, v35
	v_rcp_f32_e32 v36, v36
	v_rcp_f32_e32 v37, v37
	v_pk_mul_f32 v[16:17], v[12:13], v[16:17]
	v_pk_mul_f32 v[20:21], v[14:15], v[20:21]
	v_pk_mul_f32 v[26:27], v[8:9], v[26:27]
	v_pk_mul_f32 v[28:29], v[10:11], v[28:29]
	v_pk_mul_f32 v[30:31], v[4:5], v[30:31]
	v_pk_mul_f32 v[32:33], v[6:7], v[32:33]
	v_pk_mul_f32 v[34:35], v[0:1], v[34:35]
	v_pk_mul_f32 v[36:37], v[2:3], v[36:37]
	v_pk_mul_f32 v[18:19], v[16:17], v[16:17]
	v_pk_mul_f32 v[22:23], v[20:21], v[20:21]
	v_add_f32_e32 v18, v18, v19
	v_add_f32_e32 v18, v22, v18
	v_pk_mul_f32 v[38:39], v[26:27], v[26:27]
	v_add_f32_e32 v18, v23, v18
	v_add_f32_e32 v18, v38, v18
	v_pk_mul_f32 v[40:41], v[28:29], v[28:29]
	v_add_f32_e32 v18, v39, v18
	v_add_f32_e32 v18, v40, v18
	v_pk_mul_f32 v[42:43], v[30:31], v[30:31]
	v_add_f32_e32 v18, v41, v18
	v_add_f32_e32 v18, v18, v42
	v_pk_mul_f32 v[44:45], v[32:33], v[32:33]
	v_add_f32_e32 v18, v43, v18
	v_add_f32_e32 v18, v44, v18
	v_pk_mul_f32 v[46:47], v[34:35], v[34:35]
	v_add_f32_e32 v18, v45, v18
	v_add_f32_e32 v18, v46, v18
	v_pk_mul_f32 v[48:49], v[36:37], v[36:37]
	v_add_f32_e32 v18, v47, v18
	v_add_f32_e32 v18, v48, v18
	v_add_f32_e32 v18, v49, v18
	ds_bpermute_b32 v19, v229, v18
	v_lshl_add_u64 v[48:49], v[140:141], 2, s[18:19]
	v_ashrrev_i32_e32 v25, 31, v24
	v_lshlrev_b64 v[42:43], 10, v[24:25]
	v_lshlrev_b32_e32 v40, 9, v24
	s_waitcnt lgkmcnt(0)
	v_add_f32_e32 v18, v18, v19
	ds_bpermute_b32 v19, v230, v18
	v_mov_b32_e32 v41, v141
	s_waitcnt lgkmcnt(0)
	v_add_f32_e32 v18, v18, v19
	v_fmamk_f32 v18, v18, 0x3c800000, v188
	v_cmp_gt_f32_e32 vcc, s13, v18
	v_mul_f32_e32 v19, 0x4b800000, v18
	s_nop 0
	v_cndmask_b32_e32 v18, v18, v19, vcc
	v_rsq_f32_e32 v18, v18
	s_nop 0
	v_mul_f32_e32 v19, 0x45800000, v18
	v_cndmask_b32_e32 v38, v18, v19, vcc
	v_pk_mul_f32 v[44:45], v[16:17], v[38:39] op_sel_hi:[1,0]
	v_pk_mul_f32 v[46:47], v[20:21], v[38:39] op_sel_hi:[1,0]
	v_mov_b64_e32 v[16:17], v[208:209]
	v_mov_b64_e32 v[18:19], v[210:211]
	v_mov_b64_e32 v[20:21], v[204:205]
	v_mov_b64_e32 v[22:23], v[206:207]
	v_pk_mul_f32 v[26:27], v[26:27], v[38:39] op_sel_hi:[1,0]
	v_pk_mul_f32 v[28:29], v[28:29], v[38:39] op_sel_hi:[1,0]
	v_pk_mul_f32 v[16:17], v[16:17], v[26:27]
	v_lshl_add_u64 v[26:27], s[46:47], 0, v[42:43]
	v_pk_mul_f32 v[22:23], v[22:23], v[46:47]
	v_pk_mul_f32 v[20:21], v[20:21], v[44:45]
	v_pk_mul_f32 v[18:19], v[18:19], v[28:29]
	v_lshl_add_u64 v[28:29], v[140:141], 1, v[26:27]
	v_lshl_add_u64 v[26:27], v[40:41], 2, s[56:57]
	v_cvt_pk_bf16_f32 v42, v20, v21
	v_cvt_pk_bf16_f32 v43, v22, v23
	v_cvt_pk_bf16_f32 v44, v16, v17
	v_cvt_pk_bf16_f32 v45, v18, v19
	v_mov_b64_e32 v[196:197], v[42:43]
	v_mov_b64_e32 v[198:199], v[44:45]
	s_and_saveexec_b64 s[0:1], s[10:11]
	s_cbranch_execz .LBB0_348
	v_lshl_add_u64 v[40:41], v[140:141], 2, v[26:27]
	v_lshl_add_u64 v[42:43], v[40:41], 0, s[70:71]
	v_add_co_u32_e32 v40, vcc, 0x2108000, v40
	s_nop 1
	v_addc_co_u32_e32 v41, vcc, 0, v41, vcc
	global_store_dwordx4 v[40:41], v[20:23], off
	global_store_dwordx4 v[42:43], v[16:19], off offset:16
; __device__ __forceinline__ void st_bf16x8(bf16_t* p, const f32x4 a, const f32x4 b) { uint4 o; o.x = cvt_pk_bf16(a[0], a[1]); o.y = cvt_pk_bf16(a[2], a[3]); o.z = cvt_pk_bf16(b[0], b[1]); o.w = cvt_pk_bf16(b[2], b[3]); *(uint4*)p = o; }
;     __device__ __forceinline__ void row(const f32x4 (&a)[2][2], int row, int pn, int wc, int fq) const {
;     ...
;             for (int bj = 0; bj < 2; ++bj) { const int d = head * 64 + bj * 32 + 8 * fq;
;                 const f32x4 v0 = g[bj][0] * rs * *(const f32x4*)(g_v + d), v1 = g[bj][1] * rs * *(const f32x4*)(g_v + d + 4);
;                 st_bf16x8(pV + (size_t)row * 512 + d, v0, v1);
;                 if (row >= NP && row < NTOK) { float* o = out + O_VS + (size_t)(row - NP) * 512 + d; *(f32x4*)o = v0; *(f32x4*)(o + 4) = v1; } }
.LBB0_348:
	s_or_b64 exec, exec, s[0:1]
	v_mov_b64_e32 v[16:17], v[212:213]
	v_mov_b64_e32 v[18:19], v[214:215]
	v_mov_b64_e32 v[20:21], v[216:217]
	v_mov_b64_e32 v[22:23], v[218:219]
	v_mov_b32_e32 v39, v38
	v_mov_b32_e32 v40, v38
	v_mov_b32_e32 v41, v38
	v_pk_mul_f32 v[30:31], v[30:31], v[38:39]
	v_pk_mul_f32 v[32:33], v[32:33], v[40:41]
	v_pk_mul_f32 v[34:35], v[34:35], v[38:39]
	v_pk_mul_f32 v[36:37], v[36:37], v[40:41]
	v_pk_mul_f32 v[18:19], v[32:33], v[18:19]
	v_pk_mul_f32 v[16:17], v[30:31], v[16:17]
	v_pk_mul_f32 v[22:23], v[36:37], v[22:23]
	v_pk_mul_f32 v[20:21], v[34:35], v[20:21]
	v_cvt_pk_bf16_f32 v30, v16, v17
	v_cvt_pk_bf16_f32 v31, v18, v19
	v_cvt_pk_bf16_f32 v33, v22, v23
	s_nop 0
	v_cvt_pk_bf16_f32 v32, v20, v21
	s_mov_b64 s[100:101], vcc
	v_and_b32_e32 v222, 1, v24
	s_movk_i32 s32, 0xfc40
	v_mad_i64_i32 v[28:29], s[98:99], v222, s32, v[28:29]
	v_cmp_eq_u32_e32 vcc, 0, v222
	s_nop 1
	v_cndmask_b32_dpp v200, v30, v196, vcc quad_perm:[1,0,3,2] row_mask:0xf bank_mask:0xf
	v_cndmask_b32_dpp v201, v31, v197, vcc quad_perm:[1,0,3,2] row_mask:0xf bank_mask:0xf
	v_cndmask_b32_dpp v202, v32, v198, vcc quad_perm:[1,0,3,2] row_mask:0xf bank_mask:0xf
	v_cndmask_b32_dpp v203, v33, v199, vcc quad_perm:[1,0,3,2] row_mask:0xf bank_mask:0xf
	v_cmp_ne_u32_e32 vcc, 0, v222
	s_nop 1
	v_cndmask_b32_dpp v30, v196, v30, vcc quad_perm:[1,0,3,2] row_mask:0xf bank_mask:0xf
	v_cndmask_b32_dpp v31, v197, v31, vcc quad_perm:[1,0,3,2] row_mask:0xf bank_mask:0xf
	v_cndmask_b32_dpp v32, v198, v32, vcc quad_perm:[1,0,3,2] row_mask:0xf bank_mask:0xf
	v_cndmask_b32_dpp v33, v199, v33, vcc quad_perm:[1,0,3,2] row_mask:0xf bank_mask:0xf
	global_store_dwordx4 v[28:29], v[200:203], off
	global_store_dwordx4 v[28:29], v[30:33], off offset:1024
	s_mov_b64 vcc, s[100:101]
	s_and_saveexec_b64 s[0:1], s[10:11]
	s_cbranch_execz .LBB0_350
	v_lshl_add_u64 v[26:27], v[152:153], 2, v[26:27]
	v_lshl_add_u64 v[28:29], v[26:27], 0, s[70:71]
	v_add_co_u32_e32 v26, vcc, 0x2108000, v26
	s_nop 1
	v_addc_co_u32_e32 v27, vcc, 0, v27, vcc
	global_store_dwordx4 v[26:27], v[16:19], off
	global_store_dwordx4 v[28:29], v[20:23], off offset:16
